# speedup vs baseline: 1.0978x; 1.0053x over previous
.LBB0_135:
	s_or_b64 exec, exec, s[18:19]
	s_and_saveexec_b64 s[10:11], s[8:9]
	v_lshlrev_b32_e32 v0, 4, v8
	s_movk_i32 s2, 0x100
	v_or3_b32 v6, v0, v7, s2
	s_or_b64 exec, exec, s[10:11]
	v_ashrrev_i32_e32 v0, 6, v4
	v_add_u32_e32 v226, s35, v0
	s_movk_i32 s2, 0x4000
	v_cmp_gt_i32_e32 vcc, s2, v226
	s_and_saveexec_b64 s[8:9], vcc
	s_cbranch_execz .LBB0_213
	v_readlane_b32 s12, v254, 29
	s_movk_i32 s2, 0xe00
	v_readlane_b32 s14, v254, 31
	s_waitcnt vmcnt(1)
	v_mul_lo_u32 v12, v0, s2
	v_readlane_b32 s15, v254, 32
	s_add_u32 s2, s14, s6
	s_addc_u32 s10, s15, s7
	s_add_u32 s6, s2, 0x187c0000
	s_addc_u32 s7, s10, 0
	v_readlane_b32 s13, v254, 30
	s_add_u32 s12, s2, 0x1c7c0000
	s_addc_u32 s13, s10, 0
	s_add_u32 s14, s2, 0x1e7c0000
	s_addc_u32 s15, s10, 0
	s_add_u32 s16, s2, 0x27c0000
	s_addc_u32 s17, s10, 0
	s_add_u32 s18, s2, 0x147c0000
	s_addc_u32 s19, s10, 0
	s_add_u32 s20, s2, 0x107c0000
	s_addc_u32 s21, s10, 0
	s_mov_b32 s10, 0
	v_cvt_f64_u32_e32 v[8:9], v226
	s_mov_b32 s11, 0x40cfff80
	v_min_f64 v[8:9], v[8:9], s[10:11]
	v_cvt_i32_f64_e32 v8, v[8:9]
	v_ashrrev_i32_e32 v9, 31, v8
	v_and_b32_e32 v7, 63, v4
	v_lshlrev_b64 v[8:9], 12, v[8:9]
	v_lshl_add_u64 v[8:9], s[6:7], 0, v[8:9]
	v_lshlrev_b32_e32 v10, 3, v7
	v_mov_b32_e32 v11, v1
	v_lshl_add_u64 v[8:9], v[8:9], 0, v[10:11]
	global_load_dwordx2 v[96:97], v[8:9], off offset:3584
	global_load_dwordx2 v[98:99], v[8:9], off offset:3072
	global_load_dwordx2 v[100:101], v[8:9], off offset:2560
	global_load_dwordx2 v[102:103], v[8:9], off offset:2048
	global_load_dwordx2 v[104:105], v[8:9], off offset:1536
	global_load_dwordx2 v[106:107], v[8:9], off offset:1024
	global_load_dwordx2 v[108:109], v[8:9], off offset:512
	global_load_dwordx2 v[110:111], v[8:9], off
	v_and_b32_e32 v0, 64, v180
	v_lshlrev_b32_e32 v8, 7, v83
	v_mov_b32_e32 v9, v1
	v_lshlrev_b32_e32 v14, 3, v83
	v_and_or_b32 v156, v4, 48, v0
	v_lshl_add_u64 v[88:89], s[22:23], 0, v[8:9]
	v_and_b32_e32 v8, 15, v2
	v_xor_b32_e32 v155, 0x7f, v83
	v_xor_b32_e32 v159, 0x6f, v83
	v_xor_b32_e32 v160, 0x5f, v83
	v_xor_b32_e32 v161, 0x4f, v83
	v_xor_b32_e32 v162, 0x3f, v83
	v_xor_b32_e32 v163, 0x2f, v83
	v_xor_b32_e32 v164, 0x1f, v83
	v_xor_b32_e32 v165, 0xf, v83
	v_bfe_u32 v9, v2, 4, 4
	v_or_b32_e32 v14, v156, v8
	v_lshlrev_b32_e32 v166, 2, v14
	v_or_b32_e32 v14, v156, v9
	v_lshlrev_b32_e32 v167, 2, v14
	v_and_b32_e32 v2, 0x100, v2
	v_and_b32_e32 v14, 15, v3
	v_cmp_ne_u32_e64 s[46:47], 0, v2
	v_bfe_u32 v15, v3, 4, 4
	v_or_b32_e32 v2, v156, v14
	v_lshlrev_b32_e32 v168, 2, v2
	v_or_b32_e32 v2, v156, v15
	v_lshlrev_b32_e32 v169, 2, v2
	v_and_b32_e32 v2, 0x100, v3
	s_waitcnt vmcnt(8)
	v_and_b32_e32 v16, 15, v5
	v_cmp_ne_u32_e64 s[48:49], 0, v2
	v_bfe_u32 v17, v5, 4, 4
	v_or_b32_e32 v2, v156, v16
	v_lshlrev_b32_e32 v203, 2, v2
	v_or_b32_e32 v2, v156, v17
	v_lshlrev_b32_e32 v204, 2, v2
	v_and_b32_e32 v2, 0x100, v5
	v_and_b32_e32 v5, 15, v6
	v_cmp_ne_u32_e64 s[50:51], 0, v2
	v_bfe_u32 v18, v6, 4, 4
	v_or_b32_e32 v2, v156, v5
	v_lshlrev_b32_e32 v205, 2, v2
	v_or_b32_e32 v2, v156, v18
	v_lshlrev_b32_e32 v206, 2, v2
	v_and_b32_e32 v2, 0x100, v6
	v_cmp_lt_i32_e32 vcc, v183, v182
	v_cmp_ne_u32_e64 s[52:53], 0, v2
	v_bfe_u32 v125, v4, 4, 2
	v_cndmask_b32_e32 v2, v180, v183, vcc
	v_cmp_lt_i32_e32 vcc, v184, v182
	v_lshlrev_b32_e32 v207, 2, v2
	v_lshl_add_u32 v13, v125, 8, v12
	v_cndmask_b32_e32 v2, v180, v184, vcc
	v_cmp_lt_i32_e32 vcc, v185, v182
	v_lshlrev_b32_e32 v208, 2, v2
	s_cmp_gt_i32 s0, 2
	v_cndmask_b32_e32 v2, v180, v185, vcc
	v_cmp_lt_i32_e32 vcc, v186, v182
	v_lshlrev_b32_e32 v209, 2, v2
	v_mov_b32_e32 v3, v1
	v_cndmask_b32_e32 v2, v180, v186, vcc
	v_cmp_lt_i32_e32 vcc, v187, v182
	v_lshlrev_b32_e32 v210, 2, v2
	s_movk_i32 s0, 0xff04
	v_cndmask_b32_e32 v2, v180, v187, vcc
	v_cmp_lt_i32_e32 vcc, v188, v182
	v_lshlrev_b32_e32 v211, 2, v2
	v_lshlrev_b32_e32 v82, 5, v83
	v_cndmask_b32_e32 v2, v180, v188, vcc
	v_lshlrev_b32_e32 v212, 2, v2
	v_lshlrev_b32_e32 v2, 6, v83
	v_mul_i32_i24_e32 v4, 0xffffff04, v125
	v_lshlrev_b32_e32 v0, 4, v83
	v_lshl_add_u64 v[90:91], s[16:17], 0, v[2:3]
	v_lshl_or_b32 v217, v125, 2, v12
	v_mad_i32_i24 v2, v125, s0, v13
	v_lshl_or_b32 v154, v7, 2, v12
	v_mov_b32_e32 v158, 0
	v_lshlrev_b32_e32 v157, 2, v156
	v_lshl_add_u64 v[84:85], s[12:13], 0, v[0:1]
	v_cmp_eq_u32_e64 s[44:45], 0, v83
	v_lshl_add_u64 v[86:87], s[14:15], 0, v[0:1]
	s_cselect_b64 s[22:23], -1, 0
	v_cmp_gt_u32_e64 s[54:55], 16, v7
	v_lshl_or_b32 v213, v8, 4, v9
	v_lshl_or_b32 v214, v14, 4, v15
	v_lshl_or_b32 v215, v16, 4, v17
	v_lshl_or_b32 v216, v5, 4, v18
	v_lshl_add_u64 v[92:93], s[6:7], 0, v[10:11]
	v_add_u32_e32 v218, 0x8000, v13
	v_add_u32_e32 v219, 0x8080, v13
	v_or_b32_e32 v220, 0x4000, v82
	v_add_u32_e32 v221, 0x8c00, v2
	v_add_u32_e32 v222, 0x8a30, v217
	v_add_u32_e32 v223, 0x8800, v2
	s_mov_b64 s[58:59], 0
	v_add_u32_e32 v224, v13, v4
	v_mov_b32_e32 v225, 0
	s_waitcnt vmcnt(0)
	s_branch .LBB0_141

.LBB0_141:
	v_cvt_pk_bf16_f32 v2, v110, v111
	v_cvt_pk_bf16_f32 v3, v108, v109
	ds_write2st64_b32 v154, v2, v3 offset0:128 offset1:129
	v_cvt_pk_bf16_f32 v2, v106, v107
	v_cvt_pk_bf16_f32 v3, v104, v105
	ds_write2st64_b32 v154, v2, v3 offset0:130 offset1:131
	v_cvt_pk_bf16_f32 v2, v102, v103
	v_cvt_pk_bf16_f32 v3, v100, v101
	ds_write2st64_b32 v154, v2, v3 offset0:132 offset1:133
	v_cvt_pk_bf16_f32 v2, v98, v99
	v_cvt_pk_bf16_f32 v3, v96, v97
	v_ashrrev_i32_e32 v95, 31, v226
	v_mov_b32_e32 v94, v226
	ds_write2st64_b32 v154, v2, v3 offset0:134 offset1:135
	v_lshlrev_b64 v[2:3], 11, v[94:95]
	v_lshl_add_u64 v[2:3], v[90:91], 0, v[2:3]
	global_load_dwordx4 v[38:41], v[2:3], off offset:48
	global_load_dwordx4 v[46:49], v[2:3], off offset:32
	global_load_dwordx4 v[50:53], v[2:3], off offset:16
	global_load_dwordx4 v[54:57], v[2:3], off
	global_load_dwordx4 v[26:29], v[2:3], off offset:1072
	global_load_dwordx4 v[30:33], v[2:3], off offset:1056
	global_load_dwordx4 v[34:37], v[2:3], off offset:1040
	global_load_dwordx4 v[42:45], v[2:3], off offset:1024
	v_lshlrev_b32_e32 v61, 2, v180
	v_sub_u32_e32 v58, v154, v61
	v_and_b32_e32 v61, 1, v83
	v_lshl_add_u32 v58, v61, 10, v58
	v_lshrrev_b32_e32 v61, 2, v83
	v_lshl_add_u32 v58, v61, 8, v58
	v_lshrrev_b32_e32 v61, 4, v180
	v_lshl_add_u32 v58, v61, 4, v58
	v_and_b32_e32 v59, 7, v83
	v_xor_b32_e32 v59, v59, v61
	v_lshlrev_b32_e32 v59, 4, v59
	v_lshl_add_u32 v59, v83, 7, v59
	v_xor_b32_e32 v60, 64, v59
	ds_read_b128 v[62:65], v58 offset:32768
	ds_read_b128 v[66:69], v58 offset:32832
	ds_read_b128 v[70:73], v58 offset:32896
	ds_read_b128 v[74:77], v58 offset:32960
	ds_read_b128 v[78:81], v59 offset:0
	ds_read_b128 v[196:199], v60 offset:0
	ds_read_b128 v[230:233], v59 offset:2048
	ds_read_b128 v[234:237], v60 offset:2048
	s_waitcnt lgkmcnt(2)
	v_mfma_f32_16x16x32_bf16 v[112:115], v[62:65], v[78:81], 0
	v_mfma_f32_16x16x32_bf16 v[112:115], v[66:69], v[196:199], v[112:115]
	ds_read_b128 v[78:81], v59 offset:4096
	ds_read_b128 v[196:199], v60 offset:4096
	s_waitcnt lgkmcnt(2)
	v_mfma_f32_16x16x32_bf16 v[116:119], v[62:65], v[230:233], 0
	v_mfma_f32_16x16x32_bf16 v[116:119], v[66:69], v[234:237], v[116:119]
	ds_read_b128 v[230:233], v59 offset:6144
	ds_read_b128 v[234:237], v60 offset:6144
	s_waitcnt lgkmcnt(2)
	v_mfma_f32_16x16x32_bf16 v[120:123], v[62:65], v[78:81], 0
	v_mfma_f32_16x16x32_bf16 v[120:123], v[66:69], v[196:199], v[120:123]
	ds_read_b128 v[78:81], v59 offset:8192
	ds_read_b128 v[196:199], v60 offset:8192
	s_waitcnt lgkmcnt(2)
	v_mfma_f32_16x16x32_bf16 v[126:129], v[62:65], v[230:233], 0
	v_mfma_f32_16x16x32_bf16 v[126:129], v[66:69], v[234:237], v[126:129]
	ds_read_b128 v[230:233], v59 offset:10240
	ds_read_b128 v[234:237], v60 offset:10240
	s_waitcnt lgkmcnt(2)
	v_mfma_f32_16x16x32_bf16 v[130:133], v[62:65], v[78:81], 0
	v_mfma_f32_16x16x32_bf16 v[130:133], v[66:69], v[196:199], v[130:133]
	ds_read_b128 v[78:81], v59 offset:12288
	ds_read_b128 v[196:199], v60 offset:12288
	s_waitcnt lgkmcnt(2)
	v_mfma_f32_16x16x32_bf16 v[134:137], v[62:65], v[230:233], 0
	v_mfma_f32_16x16x32_bf16 v[134:137], v[66:69], v[234:237], v[134:137]
	ds_read_b128 v[230:233], v59 offset:14336
	ds_read_b128 v[234:237], v60 offset:14336
	s_waitcnt lgkmcnt(2)
	v_mfma_f32_16x16x32_bf16 v[138:141], v[62:65], v[78:81], 0
	v_mfma_f32_16x16x32_bf16 v[138:141], v[66:69], v[196:199], v[138:141]
	ds_read_b128 v[78:81], v59 offset:16384
	ds_read_b128 v[196:199], v60 offset:16384
	s_waitcnt lgkmcnt(2)
	v_mfma_f32_16x16x32_bf16 v[142:145], v[62:65], v[230:233], 0
	v_mfma_f32_16x16x32_bf16 v[142:145], v[66:69], v[234:237], v[142:145]
	ds_read_b128 v[230:233], v59 offset:18432
	ds_read_b128 v[234:237], v60 offset:18432
	s_waitcnt lgkmcnt(2)
	v_mfma_f32_16x16x32_bf16 v[146:149], v[70:73], v[78:81], 0
	v_mfma_f32_16x16x32_bf16 v[146:149], v[74:77], v[196:199], v[146:149]
	ds_read_b128 v[78:81], v59 offset:20480
	ds_read_b128 v[196:199], v60 offset:20480
	s_waitcnt lgkmcnt(2)
	v_mfma_f32_16x16x32_bf16 v[150:153], v[70:73], v[230:233], 0
	v_mfma_f32_16x16x32_bf16 v[150:153], v[74:77], v[234:237], v[150:153]
	ds_read_b128 v[230:233], v59 offset:22528
	ds_read_b128 v[234:237], v60 offset:22528
	s_waitcnt lgkmcnt(2)
	v_mfma_f32_16x16x32_bf16 v[98:101], v[70:73], v[78:81], 0
	v_mfma_f32_16x16x32_bf16 v[98:101], v[74:77], v[196:199], v[98:101]
	ds_read_b128 v[78:81], v59 offset:24576
	ds_read_b128 v[196:199], v60 offset:24576
	s_waitcnt lgkmcnt(2)
	v_mfma_f32_16x16x32_bf16 v[102:105], v[70:73], v[230:233], 0
	v_mfma_f32_16x16x32_bf16 v[102:105], v[74:77], v[234:237], v[102:105]
	ds_read_b128 v[230:233], v59 offset:26624
	ds_read_b128 v[234:237], v60 offset:26624
	s_waitcnt lgkmcnt(2)
	v_mfma_f32_16x16x32_bf16 v[106:109], v[70:73], v[78:81], 0
	v_mfma_f32_16x16x32_bf16 v[106:109], v[74:77], v[196:199], v[106:109]
	ds_read_b128 v[78:81], v59 offset:28672
	ds_read_b128 v[196:199], v60 offset:28672
	s_waitcnt lgkmcnt(2)
	v_mfma_f32_16x16x32_bf16 v[238:241], v[70:73], v[230:233], 0
	v_mfma_f32_16x16x32_bf16 v[238:241], v[74:77], v[234:237], v[238:241]
	ds_read_b128 v[230:233], v59 offset:30720
	ds_read_b128 v[234:237], v60 offset:30720
	s_waitcnt lgkmcnt(2)
	v_mfma_f32_16x16x32_bf16 v[242:245], v[70:73], v[78:81], 0
	v_mfma_f32_16x16x32_bf16 v[242:245], v[74:77], v[196:199], v[242:245]
	s_waitcnt lgkmcnt(0)
	v_mfma_f32_16x16x32_bf16 v[246:249], v[70:73], v[230:233], 0
	v_mfma_f32_16x16x32_bf16 v[246:249], v[74:77], v[234:237], v[246:249]
	s_mov_b32 s0, 0
	s_mov_b64 s[6:7], -1

.LBB0_186:
	s_andn2_saveexec_b64 s[6:7], s[6:7]
	v_mul_f32_e32 v28, v26, v26
	v_fmamk_f32 v29, v28, 0xba1345e1, v171
	v_fmaak_f32 v29, v28, v29, 0xbcdac9b8
	v_fmaak_f32 v29, v28, v29, 0x3de703be
	v_fmaak_f32 v29, v28, v29, 0xbec09330
	v_fmaak_f32 v28, v28, v29, 0x3e0375d0
	v_fma_f32 v28, |v26|, v28, |v26|
	s_or_b64 exec, exec, s[6:7]
	ds_read_b32 v29, v154 offset:35072
	s_brev_b32 s0, -2
	v_bfi_b32 v26, s0, v28, v26
	v_mul_f32_e32 v27, 0.5, v27
	v_add_f32_e32 v26, 1.0, v26
	v_mul_f32_e32 v26, v27, v26
	v_mul_f32_e32 v26, 0x3d353d2b, v26
	s_waitcnt vmcnt(2)
	s_waitcnt lgkmcnt(0)
	v_mul_f32_e32 v26, v29, v26
	s_mov_b32 s2, -4
	v_mov_b32_e32 v131, v222
	v_mov_b32_e32 v132, v223
	s_waitcnt vmcnt(0)
	ds_write_b32 v154, v26 offset:35072
	ds_read_b32 v30, v217 offset:35376
	ds_read_b32 v142, v217 offset:35392
	ds_read_b32 v150, v217 offset:35408
	ds_read_b32 v236, v217 offset:35424
	ds_read_b32 v250, v217 offset:35440
	s_movk_i32 s0, 0x200
	s_waitcnt lgkmcnt(0)
	v_mad_u64_u32 v[248:249], vcc, v30, s0, v[86:87]
	global_load_dwordx4 v[30:33], v[248:249], off
	global_load_dwordx4 v[26:29], v[248:249], off offset:256
	v_mad_u64_u32 v[248:249], vcc, v142, s0, v[86:87]
	global_load_dwordx4 v[142:145], v[248:249], off
	global_load_dwordx4 v[146:149], v[248:249], off offset:256
	v_mad_u64_u32 v[248:249], vcc, v150, s0, v[86:87]
	global_load_dwordx4 v[150:153], v[248:249], off
	global_load_dwordx4 v[232:235], v[248:249], off offset:256
	v_mad_u64_u32 v[248:249], vcc, v236, s0, v[86:87]
	global_load_dwordx4 v[236:239], v[248:249], off
	global_load_dwordx4 v[240:243], v[248:249], off offset:256
	v_add_u32_e32 v131, 0x8a80, v217
	v_mov_b32_e32 v132, v223
	s_mov_b32 s2, 0
	v_mad_u64_u32 v[248:249], vcc, v250, s0, v[86:87]
	global_load_dwordx4 v[244:247], v[248:249], off
	global_load_dwordx4 v[228:231], v[248:249], off offset:256
	ds_read_b32 v227, v131 offset:0
	ds_read_b32 v130, v132 offset:0
	s_waitcnt vmcnt(15)
	v_cvt_scalef32_pk_f32_fp4 v[134:135], v10, 1.0
	v_cvt_scalef32_pk_f32_fp4 v[136:137], v10, 1.0 op_sel:[1,0,0]
	v_cvt_scalef32_pk_f32_fp4 v[138:139], v10, 1.0 op_sel:[0,1,0]
	v_cvt_scalef32_pk_f32_fp4 v[140:141], v10, 1.0 op_sel:[1,1,0]
	s_waitcnt lgkmcnt(0)
	v_pk_mul_f32 v[128:129], v[130:131], v[134:135] op_sel_hi:[0,1]
	v_pk_mul_f32 v[126:127], v[130:131], v[136:137] op_sel_hi:[0,1]
	v_pk_mul_f32 v[122:123], v[130:131], v[138:139] op_sel_hi:[0,1]
	v_pk_mul_f32 v[120:121], v[130:131], v[140:141] op_sel_hi:[0,1]
	v_cvt_scalef32_pk_f32_fp4 v[134:135], v11, 1.0
	v_cvt_scalef32_pk_f32_fp4 v[136:137], v11, 1.0 op_sel:[1,0,0]
	v_cvt_scalef32_pk_f32_fp4 v[138:139], v11, 1.0 op_sel:[0,1,0]
	v_cvt_scalef32_pk_f32_fp4 v[140:141], v11, 1.0 op_sel:[1,1,0]
	v_pk_mul_f32 v[118:119], v[130:131], v[134:135] op_sel_hi:[0,1]
	v_pk_mul_f32 v[116:117], v[130:131], v[136:137] op_sel_hi:[0,1]
	v_pk_mul_f32 v[114:115], v[130:131], v[138:139] op_sel_hi:[0,1]
	v_pk_mul_f32 v[112:113], v[130:131], v[140:141] op_sel_hi:[0,1]
	v_cvt_scalef32_pk_f32_fp4 v[134:135], v12, 1.0
	v_cvt_scalef32_pk_f32_fp4 v[136:137], v12, 1.0 op_sel:[1,0,0]
	v_cvt_scalef32_pk_f32_fp4 v[138:139], v12, 1.0 op_sel:[0,1,0]
	v_cvt_scalef32_pk_f32_fp4 v[140:141], v12, 1.0 op_sel:[1,1,0]
	v_pk_mul_f32 v[80:81], v[130:131], v[134:135] op_sel_hi:[0,1]
	v_pk_mul_f32 v[78:79], v[130:131], v[136:137] op_sel_hi:[0,1]
	v_pk_mul_f32 v[76:77], v[130:131], v[138:139] op_sel_hi:[0,1]
	v_pk_mul_f32 v[74:75], v[130:131], v[140:141] op_sel_hi:[0,1]
	v_cvt_scalef32_pk_f32_fp4 v[134:135], v13, 1.0
	v_cvt_scalef32_pk_f32_fp4 v[136:137], v13, 1.0 op_sel:[1,0,0]
	v_cvt_scalef32_pk_f32_fp4 v[138:139], v13, 1.0 op_sel:[0,1,0]
	v_cvt_scalef32_pk_f32_fp4 v[140:141], v13, 1.0 op_sel:[1,1,0]
	v_pk_mul_f32 v[72:73], v[130:131], v[134:135] op_sel_hi:[0,1]
	v_pk_mul_f32 v[70:71], v[130:131], v[136:137] op_sel_hi:[0,1]
	v_pk_mul_f32 v[68:69], v[130:131], v[138:139] op_sel_hi:[0,1]
	v_pk_mul_f32 v[66:67], v[130:131], v[140:141] op_sel_hi:[0,1]
	s_waitcnt vmcnt(14)
	v_cvt_scalef32_pk_f32_fp4 v[134:135], v2, 1.0
	v_cvt_scalef32_pk_f32_fp4 v[136:137], v2, 1.0 op_sel:[1,0,0]
	v_cvt_scalef32_pk_f32_fp4 v[138:139], v2, 1.0 op_sel:[0,1,0]
	v_cvt_scalef32_pk_f32_fp4 v[140:141], v2, 1.0 op_sel:[1,1,0]
	v_pk_mul_f32 v[34:35], v[130:131], v[134:135] op_sel_hi:[0,1]
	v_pk_mul_f32 v[36:37], v[130:131], v[136:137] op_sel_hi:[0,1]
	v_pk_mul_f32 v[38:39], v[130:131], v[138:139] op_sel_hi:[0,1]
	v_pk_mul_f32 v[40:41], v[130:131], v[140:141] op_sel_hi:[0,1]
	v_cvt_scalef32_pk_f32_fp4 v[134:135], v3, 1.0
	v_cvt_scalef32_pk_f32_fp4 v[136:137], v3, 1.0 op_sel:[1,0,0]
	v_cvt_scalef32_pk_f32_fp4 v[138:139], v3, 1.0 op_sel:[0,1,0]
	v_cvt_scalef32_pk_f32_fp4 v[140:141], v3, 1.0 op_sel:[1,1,0]
	v_pk_mul_f32 v[42:43], v[130:131], v[134:135] op_sel_hi:[0,1]
	v_pk_mul_f32 v[44:45], v[130:131], v[136:137] op_sel_hi:[0,1]
	v_pk_mul_f32 v[46:47], v[130:131], v[138:139] op_sel_hi:[0,1]
	v_pk_mul_f32 v[48:49], v[130:131], v[140:141] op_sel_hi:[0,1]
	v_cvt_scalef32_pk_f32_fp4 v[134:135], v4, 1.0
	v_cvt_scalef32_pk_f32_fp4 v[136:137], v4, 1.0 op_sel:[1,0,0]
	v_cvt_scalef32_pk_f32_fp4 v[138:139], v4, 1.0 op_sel:[0,1,0]
	v_cvt_scalef32_pk_f32_fp4 v[140:141], v4, 1.0 op_sel:[1,1,0]
	v_pk_mul_f32 v[50:51], v[130:131], v[134:135] op_sel_hi:[0,1]
	v_pk_mul_f32 v[52:53], v[130:131], v[136:137] op_sel_hi:[0,1]
	v_pk_mul_f32 v[54:55], v[130:131], v[138:139] op_sel_hi:[0,1]
	v_pk_mul_f32 v[56:57], v[130:131], v[140:141] op_sel_hi:[0,1]
	v_cvt_scalef32_pk_f32_fp4 v[134:135], v5, 1.0
	v_cvt_scalef32_pk_f32_fp4 v[136:137], v5, 1.0 op_sel:[1,0,0]
	v_cvt_scalef32_pk_f32_fp4 v[138:139], v5, 1.0 op_sel:[0,1,0]
	v_cvt_scalef32_pk_f32_fp4 v[140:141], v5, 1.0 op_sel:[1,1,0]
	v_pk_mul_f32 v[58:59], v[130:131], v[134:135] op_sel_hi:[0,1]
	v_pk_mul_f32 v[60:61], v[130:131], v[136:137] op_sel_hi:[0,1]
	v_pk_mul_f32 v[62:63], v[130:131], v[138:139] op_sel_hi:[0,1]
	v_pk_mul_f32 v[64:65], v[130:131], v[140:141] op_sel_hi:[0,1]
.Lpv_loop:
	v_mad_u64_u32 v[248:249], vcc, v227, s0, v[86:87]
	global_load_dwordx4 v[10:13], v[248:249], off
	global_load_dwordx4 v[2:5], v[248:249], off offset:256
	ds_read_b32 v250, v131 offset:16
	ds_read_b32 v130, v132 offset:16
	s_waitcnt vmcnt(15)
	v_cvt_scalef32_pk_f32_fp4 v[134:135], v14, 1.0
	v_cvt_scalef32_pk_f32_fp4 v[136:137], v14, 1.0 op_sel:[1,0,0]
	v_cvt_scalef32_pk_f32_fp4 v[138:139], v14, 1.0 op_sel:[0,1,0]
	v_cvt_scalef32_pk_f32_fp4 v[140:141], v14, 1.0 op_sel:[1,1,0]
	s_waitcnt lgkmcnt(0)
	v_pk_fma_f32 v[128:129], v[130:131], v[134:135], v[128:129] op_sel_hi:[0,1,1]
	v_pk_fma_f32 v[126:127], v[130:131], v[136:137], v[126:127] op_sel_hi:[0,1,1]
	v_pk_fma_f32 v[122:123], v[130:131], v[138:139], v[122:123] op_sel_hi:[0,1,1]
	v_pk_fma_f32 v[120:121], v[130:131], v[140:141], v[120:121] op_sel_hi:[0,1,1]
	v_cvt_scalef32_pk_f32_fp4 v[134:135], v15, 1.0
	v_cvt_scalef32_pk_f32_fp4 v[136:137], v15, 1.0 op_sel:[1,0,0]
	v_cvt_scalef32_pk_f32_fp4 v[138:139], v15, 1.0 op_sel:[0,1,0]
	v_cvt_scalef32_pk_f32_fp4 v[140:141], v15, 1.0 op_sel:[1,1,0]
	v_pk_fma_f32 v[118:119], v[130:131], v[134:135], v[118:119] op_sel_hi:[0,1,1]
	v_pk_fma_f32 v[116:117], v[130:131], v[136:137], v[116:117] op_sel_hi:[0,1,1]
	v_pk_fma_f32 v[114:115], v[130:131], v[138:139], v[114:115] op_sel_hi:[0,1,1]
	v_pk_fma_f32 v[112:113], v[130:131], v[140:141], v[112:113] op_sel_hi:[0,1,1]
	v_cvt_scalef32_pk_f32_fp4 v[134:135], v16, 1.0
	v_cvt_scalef32_pk_f32_fp4 v[136:137], v16, 1.0 op_sel:[1,0,0]
	v_cvt_scalef32_pk_f32_fp4 v[138:139], v16, 1.0 op_sel:[0,1,0]
	v_cvt_scalef32_pk_f32_fp4 v[140:141], v16, 1.0 op_sel:[1,1,0]
	v_pk_fma_f32 v[80:81], v[130:131], v[134:135], v[80:81] op_sel_hi:[0,1,1]
	v_pk_fma_f32 v[78:79], v[130:131], v[136:137], v[78:79] op_sel_hi:[0,1,1]
	v_pk_fma_f32 v[76:77], v[130:131], v[138:139], v[76:77] op_sel_hi:[0,1,1]
	v_pk_fma_f32 v[74:75], v[130:131], v[140:141], v[74:75] op_sel_hi:[0,1,1]
	v_cvt_scalef32_pk_f32_fp4 v[134:135], v17, 1.0
	v_cvt_scalef32_pk_f32_fp4 v[136:137], v17, 1.0 op_sel:[1,0,0]
	v_cvt_scalef32_pk_f32_fp4 v[138:139], v17, 1.0 op_sel:[0,1,0]
	v_cvt_scalef32_pk_f32_fp4 v[140:141], v17, 1.0 op_sel:[1,1,0]
	v_pk_fma_f32 v[72:73], v[130:131], v[134:135], v[72:73] op_sel_hi:[0,1,1]
	v_pk_fma_f32 v[70:71], v[130:131], v[136:137], v[70:71] op_sel_hi:[0,1,1]
	v_pk_fma_f32 v[68:69], v[130:131], v[138:139], v[68:69] op_sel_hi:[0,1,1]
	v_pk_fma_f32 v[66:67], v[130:131], v[140:141], v[66:67] op_sel_hi:[0,1,1]
	s_waitcnt vmcnt(14)
	v_cvt_scalef32_pk_f32_fp4 v[134:135], v6, 1.0
	v_cvt_scalef32_pk_f32_fp4 v[136:137], v6, 1.0 op_sel:[1,0,0]
	v_cvt_scalef32_pk_f32_fp4 v[138:139], v6, 1.0 op_sel:[0,1,0]
	v_cvt_scalef32_pk_f32_fp4 v[140:141], v6, 1.0 op_sel:[1,1,0]
	v_pk_fma_f32 v[34:35], v[130:131], v[134:135], v[34:35] op_sel_hi:[0,1,1]
	v_pk_fma_f32 v[36:37], v[130:131], v[136:137], v[36:37] op_sel_hi:[0,1,1]
	v_pk_fma_f32 v[38:39], v[130:131], v[138:139], v[38:39] op_sel_hi:[0,1,1]
	v_pk_fma_f32 v[40:41], v[130:131], v[140:141], v[40:41] op_sel_hi:[0,1,1]
	v_cvt_scalef32_pk_f32_fp4 v[134:135], v7, 1.0
	v_cvt_scalef32_pk_f32_fp4 v[136:137], v7, 1.0 op_sel:[1,0,0]
	v_cvt_scalef32_pk_f32_fp4 v[138:139], v7, 1.0 op_sel:[0,1,0]
	v_cvt_scalef32_pk_f32_fp4 v[140:141], v7, 1.0 op_sel:[1,1,0]
	v_pk_fma_f32 v[42:43], v[130:131], v[134:135], v[42:43] op_sel_hi:[0,1,1]
	v_pk_fma_f32 v[44:45], v[130:131], v[136:137], v[44:45] op_sel_hi:[0,1,1]
	v_pk_fma_f32 v[46:47], v[130:131], v[138:139], v[46:47] op_sel_hi:[0,1,1]
	v_pk_fma_f32 v[48:49], v[130:131], v[140:141], v[48:49] op_sel_hi:[0,1,1]
	v_cvt_scalef32_pk_f32_fp4 v[134:135], v8, 1.0
	v_cvt_scalef32_pk_f32_fp4 v[136:137], v8, 1.0 op_sel:[1,0,0]
	v_cvt_scalef32_pk_f32_fp4 v[138:139], v8, 1.0 op_sel:[0,1,0]
	v_cvt_scalef32_pk_f32_fp4 v[140:141], v8, 1.0 op_sel:[1,1,0]
	v_pk_fma_f32 v[50:51], v[130:131], v[134:135], v[50:51] op_sel_hi:[0,1,1]
	v_pk_fma_f32 v[52:53], v[130:131], v[136:137], v[52:53] op_sel_hi:[0,1,1]
	v_pk_fma_f32 v[54:55], v[130:131], v[138:139], v[54:55] op_sel_hi:[0,1,1]
	v_pk_fma_f32 v[56:57], v[130:131], v[140:141], v[56:57] op_sel_hi:[0,1,1]
	v_cvt_scalef32_pk_f32_fp4 v[134:135], v9, 1.0
	v_cvt_scalef32_pk_f32_fp4 v[136:137], v9, 1.0 op_sel:[1,0,0]
	v_cvt_scalef32_pk_f32_fp4 v[138:139], v9, 1.0 op_sel:[0,1,0]
	v_cvt_scalef32_pk_f32_fp4 v[140:141], v9, 1.0 op_sel:[1,1,0]
	v_pk_fma_f32 v[58:59], v[130:131], v[134:135], v[58:59] op_sel_hi:[0,1,1]
	v_pk_fma_f32 v[60:61], v[130:131], v[136:137], v[60:61] op_sel_hi:[0,1,1]
	v_pk_fma_f32 v[62:63], v[130:131], v[138:139], v[62:63] op_sel_hi:[0,1,1]
	v_pk_fma_f32 v[64:65], v[130:131], v[140:141], v[64:65] op_sel_hi:[0,1,1]
	v_mad_u64_u32 v[248:249], vcc, v250, s0, v[86:87]
	global_load_dwordx4 v[14:17], v[248:249], off
	global_load_dwordx4 v[6:9], v[248:249], off offset:256
	ds_read_b32 v227, v131 offset:32
	ds_read_b32 v130, v132 offset:32
	s_waitcnt vmcnt(15)
	v_cvt_scalef32_pk_f32_fp4 v[134:135], v22, 1.0
	v_cvt_scalef32_pk_f32_fp4 v[136:137], v22, 1.0 op_sel:[1,0,0]
	v_cvt_scalef32_pk_f32_fp4 v[138:139], v22, 1.0 op_sel:[0,1,0]
	v_cvt_scalef32_pk_f32_fp4 v[140:141], v22, 1.0 op_sel:[1,1,0]
	s_waitcnt lgkmcnt(0)
	v_pk_fma_f32 v[128:129], v[130:131], v[134:135], v[128:129] op_sel_hi:[0,1,1]
	v_pk_fma_f32 v[126:127], v[130:131], v[136:137], v[126:127] op_sel_hi:[0,1,1]
	v_pk_fma_f32 v[122:123], v[130:131], v[138:139], v[122:123] op_sel_hi:[0,1,1]
	v_pk_fma_f32 v[120:121], v[130:131], v[140:141], v[120:121] op_sel_hi:[0,1,1]
	v_cvt_scalef32_pk_f32_fp4 v[134:135], v23, 1.0
	v_cvt_scalef32_pk_f32_fp4 v[136:137], v23, 1.0 op_sel:[1,0,0]
	v_cvt_scalef32_pk_f32_fp4 v[138:139], v23, 1.0 op_sel:[0,1,0]
	v_cvt_scalef32_pk_f32_fp4 v[140:141], v23, 1.0 op_sel:[1,1,0]
	v_pk_fma_f32 v[118:119], v[130:131], v[134:135], v[118:119] op_sel_hi:[0,1,1]
	v_pk_fma_f32 v[116:117], v[130:131], v[136:137], v[116:117] op_sel_hi:[0,1,1]
	v_pk_fma_f32 v[114:115], v[130:131], v[138:139], v[114:115] op_sel_hi:[0,1,1]
	v_pk_fma_f32 v[112:113], v[130:131], v[140:141], v[112:113] op_sel_hi:[0,1,1]
	v_cvt_scalef32_pk_f32_fp4 v[134:135], v24, 1.0
	v_cvt_scalef32_pk_f32_fp4 v[136:137], v24, 1.0 op_sel:[1,0,0]
	v_cvt_scalef32_pk_f32_fp4 v[138:139], v24, 1.0 op_sel:[0,1,0]
	v_cvt_scalef32_pk_f32_fp4 v[140:141], v24, 1.0 op_sel:[1,1,0]
	v_pk_fma_f32 v[80:81], v[130:131], v[134:135], v[80:81] op_sel_hi:[0,1,1]
	v_pk_fma_f32 v[78:79], v[130:131], v[136:137], v[78:79] op_sel_hi:[0,1,1]
	v_pk_fma_f32 v[76:77], v[130:131], v[138:139], v[76:77] op_sel_hi:[0,1,1]
	v_pk_fma_f32 v[74:75], v[130:131], v[140:141], v[74:75] op_sel_hi:[0,1,1]
	v_cvt_scalef32_pk_f32_fp4 v[134:135], v25, 1.0
	v_cvt_scalef32_pk_f32_fp4 v[136:137], v25, 1.0 op_sel:[1,0,0]
	v_cvt_scalef32_pk_f32_fp4 v[138:139], v25, 1.0 op_sel:[0,1,0]
	v_cvt_scalef32_pk_f32_fp4 v[140:141], v25, 1.0 op_sel:[1,1,0]
	v_pk_fma_f32 v[72:73], v[130:131], v[134:135], v[72:73] op_sel_hi:[0,1,1]
	v_pk_fma_f32 v[70:71], v[130:131], v[136:137], v[70:71] op_sel_hi:[0,1,1]
	v_pk_fma_f32 v[68:69], v[130:131], v[138:139], v[68:69] op_sel_hi:[0,1,1]
	v_pk_fma_f32 v[66:67], v[130:131], v[140:141], v[66:67] op_sel_hi:[0,1,1]
	s_waitcnt vmcnt(14)
	v_cvt_scalef32_pk_f32_fp4 v[134:135], v18, 1.0
	v_cvt_scalef32_pk_f32_fp4 v[136:137], v18, 1.0 op_sel:[1,0,0]
	v_cvt_scalef32_pk_f32_fp4 v[138:139], v18, 1.0 op_sel:[0,1,0]
	v_cvt_scalef32_pk_f32_fp4 v[140:141], v18, 1.0 op_sel:[1,1,0]
	v_pk_fma_f32 v[34:35], v[130:131], v[134:135], v[34:35] op_sel_hi:[0,1,1]
	v_pk_fma_f32 v[36:37], v[130:131], v[136:137], v[36:37] op_sel_hi:[0,1,1]
	v_pk_fma_f32 v[38:39], v[130:131], v[138:139], v[38:39] op_sel_hi:[0,1,1]
	v_pk_fma_f32 v[40:41], v[130:131], v[140:141], v[40:41] op_sel_hi:[0,1,1]
	v_cvt_scalef32_pk_f32_fp4 v[134:135], v19, 1.0
	v_cvt_scalef32_pk_f32_fp4 v[136:137], v19, 1.0 op_sel:[1,0,0]
	v_cvt_scalef32_pk_f32_fp4 v[138:139], v19, 1.0 op_sel:[0,1,0]
	v_cvt_scalef32_pk_f32_fp4 v[140:141], v19, 1.0 op_sel:[1,1,0]
	v_pk_fma_f32 v[42:43], v[130:131], v[134:135], v[42:43] op_sel_hi:[0,1,1]
	v_pk_fma_f32 v[44:45], v[130:131], v[136:137], v[44:45] op_sel_hi:[0,1,1]
	v_pk_fma_f32 v[46:47], v[130:131], v[138:139], v[46:47] op_sel_hi:[0,1,1]
	v_pk_fma_f32 v[48:49], v[130:131], v[140:141], v[48:49] op_sel_hi:[0,1,1]
	v_cvt_scalef32_pk_f32_fp4 v[134:135], v20, 1.0
	v_cvt_scalef32_pk_f32_fp4 v[136:137], v20, 1.0 op_sel:[1,0,0]
	v_cvt_scalef32_pk_f32_fp4 v[138:139], v20, 1.0 op_sel:[0,1,0]
	v_cvt_scalef32_pk_f32_fp4 v[140:141], v20, 1.0 op_sel:[1,1,0]
	v_pk_fma_f32 v[50:51], v[130:131], v[134:135], v[50:51] op_sel_hi:[0,1,1]
	v_pk_fma_f32 v[52:53], v[130:131], v[136:137], v[52:53] op_sel_hi:[0,1,1]
	v_pk_fma_f32 v[54:55], v[130:131], v[138:139], v[54:55] op_sel_hi:[0,1,1]
	v_pk_fma_f32 v[56:57], v[130:131], v[140:141], v[56:57] op_sel_hi:[0,1,1]
	v_cvt_scalef32_pk_f32_fp4 v[134:135], v21, 1.0
	v_cvt_scalef32_pk_f32_fp4 v[136:137], v21, 1.0 op_sel:[1,0,0]
	v_cvt_scalef32_pk_f32_fp4 v[138:139], v21, 1.0 op_sel:[0,1,0]
	v_cvt_scalef32_pk_f32_fp4 v[140:141], v21, 1.0 op_sel:[1,1,0]
	v_pk_fma_f32 v[58:59], v[130:131], v[134:135], v[58:59] op_sel_hi:[0,1,1]
	v_pk_fma_f32 v[60:61], v[130:131], v[136:137], v[60:61] op_sel_hi:[0,1,1]
	v_pk_fma_f32 v[62:63], v[130:131], v[138:139], v[62:63] op_sel_hi:[0,1,1]
	v_pk_fma_f32 v[64:65], v[130:131], v[140:141], v[64:65] op_sel_hi:[0,1,1]
	v_mad_u64_u32 v[248:249], vcc, v227, s0, v[86:87]
	global_load_dwordx4 v[22:25], v[248:249], off
	global_load_dwordx4 v[18:21], v[248:249], off offset:256
	ds_read_b32 v250, v131 offset:48
	ds_read_b32 v130, v132 offset:48
	s_waitcnt vmcnt(15)
	v_cvt_scalef32_pk_f32_fp4 v[134:135], v30, 1.0
	v_cvt_scalef32_pk_f32_fp4 v[136:137], v30, 1.0 op_sel:[1,0,0]
	v_cvt_scalef32_pk_f32_fp4 v[138:139], v30, 1.0 op_sel:[0,1,0]
	v_cvt_scalef32_pk_f32_fp4 v[140:141], v30, 1.0 op_sel:[1,1,0]
	s_waitcnt lgkmcnt(0)
	v_pk_fma_f32 v[128:129], v[130:131], v[134:135], v[128:129] op_sel_hi:[0,1,1]
	v_pk_fma_f32 v[126:127], v[130:131], v[136:137], v[126:127] op_sel_hi:[0,1,1]
	v_pk_fma_f32 v[122:123], v[130:131], v[138:139], v[122:123] op_sel_hi:[0,1,1]
	v_pk_fma_f32 v[120:121], v[130:131], v[140:141], v[120:121] op_sel_hi:[0,1,1]
	v_cvt_scalef32_pk_f32_fp4 v[134:135], v31, 1.0
	v_cvt_scalef32_pk_f32_fp4 v[136:137], v31, 1.0 op_sel:[1,0,0]
	v_cvt_scalef32_pk_f32_fp4 v[138:139], v31, 1.0 op_sel:[0,1,0]
	v_cvt_scalef32_pk_f32_fp4 v[140:141], v31, 1.0 op_sel:[1,1,0]
	v_pk_fma_f32 v[118:119], v[130:131], v[134:135], v[118:119] op_sel_hi:[0,1,1]
	v_pk_fma_f32 v[116:117], v[130:131], v[136:137], v[116:117] op_sel_hi:[0,1,1]
	v_pk_fma_f32 v[114:115], v[130:131], v[138:139], v[114:115] op_sel_hi:[0,1,1]
	v_pk_fma_f32 v[112:113], v[130:131], v[140:141], v[112:113] op_sel_hi:[0,1,1]
	v_cvt_scalef32_pk_f32_fp4 v[134:135], v32, 1.0
	v_cvt_scalef32_pk_f32_fp4 v[136:137], v32, 1.0 op_sel:[1,0,0]
	v_cvt_scalef32_pk_f32_fp4 v[138:139], v32, 1.0 op_sel:[0,1,0]
	v_cvt_scalef32_pk_f32_fp4 v[140:141], v32, 1.0 op_sel:[1,1,0]
	v_pk_fma_f32 v[80:81], v[130:131], v[134:135], v[80:81] op_sel_hi:[0,1,1]
	v_pk_fma_f32 v[78:79], v[130:131], v[136:137], v[78:79] op_sel_hi:[0,1,1]
	v_pk_fma_f32 v[76:77], v[130:131], v[138:139], v[76:77] op_sel_hi:[0,1,1]
	v_pk_fma_f32 v[74:75], v[130:131], v[140:141], v[74:75] op_sel_hi:[0,1,1]
	v_cvt_scalef32_pk_f32_fp4 v[134:135], v33, 1.0
	v_cvt_scalef32_pk_f32_fp4 v[136:137], v33, 1.0 op_sel:[1,0,0]
	v_cvt_scalef32_pk_f32_fp4 v[138:139], v33, 1.0 op_sel:[0,1,0]
	v_cvt_scalef32_pk_f32_fp4 v[140:141], v33, 1.0 op_sel:[1,1,0]
	v_pk_fma_f32 v[72:73], v[130:131], v[134:135], v[72:73] op_sel_hi:[0,1,1]
	v_pk_fma_f32 v[70:71], v[130:131], v[136:137], v[70:71] op_sel_hi:[0,1,1]
	v_pk_fma_f32 v[68:69], v[130:131], v[138:139], v[68:69] op_sel_hi:[0,1,1]
	v_pk_fma_f32 v[66:67], v[130:131], v[140:141], v[66:67] op_sel_hi:[0,1,1]
	s_waitcnt vmcnt(14)
	v_cvt_scalef32_pk_f32_fp4 v[134:135], v26, 1.0
	v_cvt_scalef32_pk_f32_fp4 v[136:137], v26, 1.0 op_sel:[1,0,0]
	v_cvt_scalef32_pk_f32_fp4 v[138:139], v26, 1.0 op_sel:[0,1,0]
	v_cvt_scalef32_pk_f32_fp4 v[140:141], v26, 1.0 op_sel:[1,1,0]
	v_pk_fma_f32 v[34:35], v[130:131], v[134:135], v[34:35] op_sel_hi:[0,1,1]
	v_pk_fma_f32 v[36:37], v[130:131], v[136:137], v[36:37] op_sel_hi:[0,1,1]
	v_pk_fma_f32 v[38:39], v[130:131], v[138:139], v[38:39] op_sel_hi:[0,1,1]
	v_pk_fma_f32 v[40:41], v[130:131], v[140:141], v[40:41] op_sel_hi:[0,1,1]
	v_cvt_scalef32_pk_f32_fp4 v[134:135], v27, 1.0
	v_cvt_scalef32_pk_f32_fp4 v[136:137], v27, 1.0 op_sel:[1,0,0]
	v_cvt_scalef32_pk_f32_fp4 v[138:139], v27, 1.0 op_sel:[0,1,0]
	v_cvt_scalef32_pk_f32_fp4 v[140:141], v27, 1.0 op_sel:[1,1,0]
	v_pk_fma_f32 v[42:43], v[130:131], v[134:135], v[42:43] op_sel_hi:[0,1,1]
	v_pk_fma_f32 v[44:45], v[130:131], v[136:137], v[44:45] op_sel_hi:[0,1,1]
	v_pk_fma_f32 v[46:47], v[130:131], v[138:139], v[46:47] op_sel_hi:[0,1,1]
	v_pk_fma_f32 v[48:49], v[130:131], v[140:141], v[48:49] op_sel_hi:[0,1,1]
	v_cvt_scalef32_pk_f32_fp4 v[134:135], v28, 1.0
	v_cvt_scalef32_pk_f32_fp4 v[136:137], v28, 1.0 op_sel:[1,0,0]
	v_cvt_scalef32_pk_f32_fp4 v[138:139], v28, 1.0 op_sel:[0,1,0]
	v_cvt_scalef32_pk_f32_fp4 v[140:141], v28, 1.0 op_sel:[1,1,0]
	v_pk_fma_f32 v[50:51], v[130:131], v[134:135], v[50:51] op_sel_hi:[0,1,1]
	v_pk_fma_f32 v[52:53], v[130:131], v[136:137], v[52:53] op_sel_hi:[0,1,1]
	v_pk_fma_f32 v[54:55], v[130:131], v[138:139], v[54:55] op_sel_hi:[0,1,1]
	v_pk_fma_f32 v[56:57], v[130:131], v[140:141], v[56:57] op_sel_hi:[0,1,1]
	v_cvt_scalef32_pk_f32_fp4 v[134:135], v29, 1.0
	v_cvt_scalef32_pk_f32_fp4 v[136:137], v29, 1.0 op_sel:[1,0,0]
	v_cvt_scalef32_pk_f32_fp4 v[138:139], v29, 1.0 op_sel:[0,1,0]
	v_cvt_scalef32_pk_f32_fp4 v[140:141], v29, 1.0 op_sel:[1,1,0]
	v_pk_fma_f32 v[58:59], v[130:131], v[134:135], v[58:59] op_sel_hi:[0,1,1]
	v_pk_fma_f32 v[60:61], v[130:131], v[136:137], v[60:61] op_sel_hi:[0,1,1]
	v_pk_fma_f32 v[62:63], v[130:131], v[138:139], v[62:63] op_sel_hi:[0,1,1]
	v_pk_fma_f32 v[64:65], v[130:131], v[140:141], v[64:65] op_sel_hi:[0,1,1]
	v_mad_u64_u32 v[248:249], vcc, v250, s0, v[86:87]
	global_load_dwordx4 v[30:33], v[248:249], off
	global_load_dwordx4 v[26:29], v[248:249], off offset:256
	ds_read_b32 v227, v131 offset:64
	ds_read_b32 v130, v132 offset:64
	s_waitcnt vmcnt(15)
	v_cvt_scalef32_pk_f32_fp4 v[134:135], v142, 1.0
	v_cvt_scalef32_pk_f32_fp4 v[136:137], v142, 1.0 op_sel:[1,0,0]
	v_cvt_scalef32_pk_f32_fp4 v[138:139], v142, 1.0 op_sel:[0,1,0]
	v_cvt_scalef32_pk_f32_fp4 v[140:141], v142, 1.0 op_sel:[1,1,0]
	s_waitcnt lgkmcnt(0)
	v_pk_fma_f32 v[128:129], v[130:131], v[134:135], v[128:129] op_sel_hi:[0,1,1]
	v_pk_fma_f32 v[126:127], v[130:131], v[136:137], v[126:127] op_sel_hi:[0,1,1]
	v_pk_fma_f32 v[122:123], v[130:131], v[138:139], v[122:123] op_sel_hi:[0,1,1]
	v_pk_fma_f32 v[120:121], v[130:131], v[140:141], v[120:121] op_sel_hi:[0,1,1]
	v_cvt_scalef32_pk_f32_fp4 v[134:135], v143, 1.0
	v_cvt_scalef32_pk_f32_fp4 v[136:137], v143, 1.0 op_sel:[1,0,0]
	v_cvt_scalef32_pk_f32_fp4 v[138:139], v143, 1.0 op_sel:[0,1,0]
	v_cvt_scalef32_pk_f32_fp4 v[140:141], v143, 1.0 op_sel:[1,1,0]
	v_pk_fma_f32 v[118:119], v[130:131], v[134:135], v[118:119] op_sel_hi:[0,1,1]
	v_pk_fma_f32 v[116:117], v[130:131], v[136:137], v[116:117] op_sel_hi:[0,1,1]
	v_pk_fma_f32 v[114:115], v[130:131], v[138:139], v[114:115] op_sel_hi:[0,1,1]
	v_pk_fma_f32 v[112:113], v[130:131], v[140:141], v[112:113] op_sel_hi:[0,1,1]
	v_cvt_scalef32_pk_f32_fp4 v[134:135], v144, 1.0
	v_cvt_scalef32_pk_f32_fp4 v[136:137], v144, 1.0 op_sel:[1,0,0]
	v_cvt_scalef32_pk_f32_fp4 v[138:139], v144, 1.0 op_sel:[0,1,0]
	v_cvt_scalef32_pk_f32_fp4 v[140:141], v144, 1.0 op_sel:[1,1,0]
	v_pk_fma_f32 v[80:81], v[130:131], v[134:135], v[80:81] op_sel_hi:[0,1,1]
	v_pk_fma_f32 v[78:79], v[130:131], v[136:137], v[78:79] op_sel_hi:[0,1,1]
	v_pk_fma_f32 v[76:77], v[130:131], v[138:139], v[76:77] op_sel_hi:[0,1,1]
	v_pk_fma_f32 v[74:75], v[130:131], v[140:141], v[74:75] op_sel_hi:[0,1,1]
	v_cvt_scalef32_pk_f32_fp4 v[134:135], v145, 1.0
	v_cvt_scalef32_pk_f32_fp4 v[136:137], v145, 1.0 op_sel:[1,0,0]
	v_cvt_scalef32_pk_f32_fp4 v[138:139], v145, 1.0 op_sel:[0,1,0]
	v_cvt_scalef32_pk_f32_fp4 v[140:141], v145, 1.0 op_sel:[1,1,0]
	v_pk_fma_f32 v[72:73], v[130:131], v[134:135], v[72:73] op_sel_hi:[0,1,1]
	v_pk_fma_f32 v[70:71], v[130:131], v[136:137], v[70:71] op_sel_hi:[0,1,1]
	v_pk_fma_f32 v[68:69], v[130:131], v[138:139], v[68:69] op_sel_hi:[0,1,1]
	v_pk_fma_f32 v[66:67], v[130:131], v[140:141], v[66:67] op_sel_hi:[0,1,1]
	s_waitcnt vmcnt(14)
	v_cvt_scalef32_pk_f32_fp4 v[134:135], v146, 1.0
	v_cvt_scalef32_pk_f32_fp4 v[136:137], v146, 1.0 op_sel:[1,0,0]
	v_cvt_scalef32_pk_f32_fp4 v[138:139], v146, 1.0 op_sel:[0,1,0]
	v_cvt_scalef32_pk_f32_fp4 v[140:141], v146, 1.0 op_sel:[1,1,0]
	v_pk_fma_f32 v[34:35], v[130:131], v[134:135], v[34:35] op_sel_hi:[0,1,1]
	v_pk_fma_f32 v[36:37], v[130:131], v[136:137], v[36:37] op_sel_hi:[0,1,1]
	v_pk_fma_f32 v[38:39], v[130:131], v[138:139], v[38:39] op_sel_hi:[0,1,1]
	v_pk_fma_f32 v[40:41], v[130:131], v[140:141], v[40:41] op_sel_hi:[0,1,1]
	v_cvt_scalef32_pk_f32_fp4 v[134:135], v147, 1.0
	v_cvt_scalef32_pk_f32_fp4 v[136:137], v147, 1.0 op_sel:[1,0,0]
	v_cvt_scalef32_pk_f32_fp4 v[138:139], v147, 1.0 op_sel:[0,1,0]
	v_cvt_scalef32_pk_f32_fp4 v[140:141], v147, 1.0 op_sel:[1,1,0]
	v_pk_fma_f32 v[42:43], v[130:131], v[134:135], v[42:43] op_sel_hi:[0,1,1]
	v_pk_fma_f32 v[44:45], v[130:131], v[136:137], v[44:45] op_sel_hi:[0,1,1]
	v_pk_fma_f32 v[46:47], v[130:131], v[138:139], v[46:47] op_sel_hi:[0,1,1]
	v_pk_fma_f32 v[48:49], v[130:131], v[140:141], v[48:49] op_sel_hi:[0,1,1]
	v_cvt_scalef32_pk_f32_fp4 v[134:135], v148, 1.0
	v_cvt_scalef32_pk_f32_fp4 v[136:137], v148, 1.0 op_sel:[1,0,0]
	v_cvt_scalef32_pk_f32_fp4 v[138:139], v148, 1.0 op_sel:[0,1,0]
	v_cvt_scalef32_pk_f32_fp4 v[140:141], v148, 1.0 op_sel:[1,1,0]
	v_pk_fma_f32 v[50:51], v[130:131], v[134:135], v[50:51] op_sel_hi:[0,1,1]
	v_pk_fma_f32 v[52:53], v[130:131], v[136:137], v[52:53] op_sel_hi:[0,1,1]
	v_pk_fma_f32 v[54:55], v[130:131], v[138:139], v[54:55] op_sel_hi:[0,1,1]
	v_pk_fma_f32 v[56:57], v[130:131], v[140:141], v[56:57] op_sel_hi:[0,1,1]
	v_cvt_scalef32_pk_f32_fp4 v[134:135], v149, 1.0
	v_cvt_scalef32_pk_f32_fp4 v[136:137], v149, 1.0 op_sel:[1,0,0]
	v_cvt_scalef32_pk_f32_fp4 v[138:139], v149, 1.0 op_sel:[0,1,0]
	v_cvt_scalef32_pk_f32_fp4 v[140:141], v149, 1.0 op_sel:[1,1,0]
	v_pk_fma_f32 v[58:59], v[130:131], v[134:135], v[58:59] op_sel_hi:[0,1,1]
	v_pk_fma_f32 v[60:61], v[130:131], v[136:137], v[60:61] op_sel_hi:[0,1,1]
	v_pk_fma_f32 v[62:63], v[130:131], v[138:139], v[62:63] op_sel_hi:[0,1,1]
	v_pk_fma_f32 v[64:65], v[130:131], v[140:141], v[64:65] op_sel_hi:[0,1,1]
	v_mad_u64_u32 v[248:249], vcc, v227, s0, v[86:87]
	global_load_dwordx4 v[142:145], v[248:249], off
	global_load_dwordx4 v[146:149], v[248:249], off offset:256
	ds_read_b32 v250, v131 offset:80
	ds_read_b32 v130, v132 offset:80
	s_waitcnt vmcnt(15)
	v_cvt_scalef32_pk_f32_fp4 v[134:135], v150, 1.0
	v_cvt_scalef32_pk_f32_fp4 v[136:137], v150, 1.0 op_sel:[1,0,0]
	v_cvt_scalef32_pk_f32_fp4 v[138:139], v150, 1.0 op_sel:[0,1,0]
	v_cvt_scalef32_pk_f32_fp4 v[140:141], v150, 1.0 op_sel:[1,1,0]
	s_waitcnt lgkmcnt(0)
	v_pk_fma_f32 v[128:129], v[130:131], v[134:135], v[128:129] op_sel_hi:[0,1,1]
	v_pk_fma_f32 v[126:127], v[130:131], v[136:137], v[126:127] op_sel_hi:[0,1,1]
	v_pk_fma_f32 v[122:123], v[130:131], v[138:139], v[122:123] op_sel_hi:[0,1,1]
	v_pk_fma_f32 v[120:121], v[130:131], v[140:141], v[120:121] op_sel_hi:[0,1,1]
	v_cvt_scalef32_pk_f32_fp4 v[134:135], v151, 1.0
	v_cvt_scalef32_pk_f32_fp4 v[136:137], v151, 1.0 op_sel:[1,0,0]
	v_cvt_scalef32_pk_f32_fp4 v[138:139], v151, 1.0 op_sel:[0,1,0]
	v_cvt_scalef32_pk_f32_fp4 v[140:141], v151, 1.0 op_sel:[1,1,0]
	v_pk_fma_f32 v[118:119], v[130:131], v[134:135], v[118:119] op_sel_hi:[0,1,1]
	v_pk_fma_f32 v[116:117], v[130:131], v[136:137], v[116:117] op_sel_hi:[0,1,1]
	v_pk_fma_f32 v[114:115], v[130:131], v[138:139], v[114:115] op_sel_hi:[0,1,1]
	v_pk_fma_f32 v[112:113], v[130:131], v[140:141], v[112:113] op_sel_hi:[0,1,1]
	v_cvt_scalef32_pk_f32_fp4 v[134:135], v152, 1.0
	v_cvt_scalef32_pk_f32_fp4 v[136:137], v152, 1.0 op_sel:[1,0,0]
	v_cvt_scalef32_pk_f32_fp4 v[138:139], v152, 1.0 op_sel:[0,1,0]
	v_cvt_scalef32_pk_f32_fp4 v[140:141], v152, 1.0 op_sel:[1,1,0]
	v_pk_fma_f32 v[80:81], v[130:131], v[134:135], v[80:81] op_sel_hi:[0,1,1]
	v_pk_fma_f32 v[78:79], v[130:131], v[136:137], v[78:79] op_sel_hi:[0,1,1]
	v_pk_fma_f32 v[76:77], v[130:131], v[138:139], v[76:77] op_sel_hi:[0,1,1]
	v_pk_fma_f32 v[74:75], v[130:131], v[140:141], v[74:75] op_sel_hi:[0,1,1]
	v_cvt_scalef32_pk_f32_fp4 v[134:135], v153, 1.0
	v_cvt_scalef32_pk_f32_fp4 v[136:137], v153, 1.0 op_sel:[1,0,0]
	v_cvt_scalef32_pk_f32_fp4 v[138:139], v153, 1.0 op_sel:[0,1,0]
	v_cvt_scalef32_pk_f32_fp4 v[140:141], v153, 1.0 op_sel:[1,1,0]
	v_pk_fma_f32 v[72:73], v[130:131], v[134:135], v[72:73] op_sel_hi:[0,1,1]
	v_pk_fma_f32 v[70:71], v[130:131], v[136:137], v[70:71] op_sel_hi:[0,1,1]
	v_pk_fma_f32 v[68:69], v[130:131], v[138:139], v[68:69] op_sel_hi:[0,1,1]
	v_pk_fma_f32 v[66:67], v[130:131], v[140:141], v[66:67] op_sel_hi:[0,1,1]
	s_waitcnt vmcnt(14)
	v_cvt_scalef32_pk_f32_fp4 v[134:135], v232, 1.0
	v_cvt_scalef32_pk_f32_fp4 v[136:137], v232, 1.0 op_sel:[1,0,0]
	v_cvt_scalef32_pk_f32_fp4 v[138:139], v232, 1.0 op_sel:[0,1,0]
	v_cvt_scalef32_pk_f32_fp4 v[140:141], v232, 1.0 op_sel:[1,1,0]
	v_pk_fma_f32 v[34:35], v[130:131], v[134:135], v[34:35] op_sel_hi:[0,1,1]
	v_pk_fma_f32 v[36:37], v[130:131], v[136:137], v[36:37] op_sel_hi:[0,1,1]
	v_pk_fma_f32 v[38:39], v[130:131], v[138:139], v[38:39] op_sel_hi:[0,1,1]
	v_pk_fma_f32 v[40:41], v[130:131], v[140:141], v[40:41] op_sel_hi:[0,1,1]
	v_cvt_scalef32_pk_f32_fp4 v[134:135], v233, 1.0
	v_cvt_scalef32_pk_f32_fp4 v[136:137], v233, 1.0 op_sel:[1,0,0]
	v_cvt_scalef32_pk_f32_fp4 v[138:139], v233, 1.0 op_sel:[0,1,0]
	v_cvt_scalef32_pk_f32_fp4 v[140:141], v233, 1.0 op_sel:[1,1,0]
	v_pk_fma_f32 v[42:43], v[130:131], v[134:135], v[42:43] op_sel_hi:[0,1,1]
	v_pk_fma_f32 v[44:45], v[130:131], v[136:137], v[44:45] op_sel_hi:[0,1,1]
	v_pk_fma_f32 v[46:47], v[130:131], v[138:139], v[46:47] op_sel_hi:[0,1,1]
	v_pk_fma_f32 v[48:49], v[130:131], v[140:141], v[48:49] op_sel_hi:[0,1,1]
	v_cvt_scalef32_pk_f32_fp4 v[134:135], v234, 1.0
	v_cvt_scalef32_pk_f32_fp4 v[136:137], v234, 1.0 op_sel:[1,0,0]
	v_cvt_scalef32_pk_f32_fp4 v[138:139], v234, 1.0 op_sel:[0,1,0]
	v_cvt_scalef32_pk_f32_fp4 v[140:141], v234, 1.0 op_sel:[1,1,0]
	v_pk_fma_f32 v[50:51], v[130:131], v[134:135], v[50:51] op_sel_hi:[0,1,1]
	v_pk_fma_f32 v[52:53], v[130:131], v[136:137], v[52:53] op_sel_hi:[0,1,1]
	v_pk_fma_f32 v[54:55], v[130:131], v[138:139], v[54:55] op_sel_hi:[0,1,1]
	v_pk_fma_f32 v[56:57], v[130:131], v[140:141], v[56:57] op_sel_hi:[0,1,1]
	v_cvt_scalef32_pk_f32_fp4 v[134:135], v235, 1.0
	v_cvt_scalef32_pk_f32_fp4 v[136:137], v235, 1.0 op_sel:[1,0,0]
	v_cvt_scalef32_pk_f32_fp4 v[138:139], v235, 1.0 op_sel:[0,1,0]
	v_cvt_scalef32_pk_f32_fp4 v[140:141], v235, 1.0 op_sel:[1,1,0]
	v_pk_fma_f32 v[58:59], v[130:131], v[134:135], v[58:59] op_sel_hi:[0,1,1]
	v_pk_fma_f32 v[60:61], v[130:131], v[136:137], v[60:61] op_sel_hi:[0,1,1]
	v_pk_fma_f32 v[62:63], v[130:131], v[138:139], v[62:63] op_sel_hi:[0,1,1]
	v_pk_fma_f32 v[64:65], v[130:131], v[140:141], v[64:65] op_sel_hi:[0,1,1]
	v_mad_u64_u32 v[248:249], vcc, v250, s0, v[86:87]
	global_load_dwordx4 v[150:153], v[248:249], off
	global_load_dwordx4 v[232:235], v[248:249], off offset:256
	ds_read_b32 v227, v131 offset:96
	ds_read_b32 v130, v132 offset:96
	s_waitcnt vmcnt(15)
	v_cvt_scalef32_pk_f32_fp4 v[134:135], v236, 1.0
	v_cvt_scalef32_pk_f32_fp4 v[136:137], v236, 1.0 op_sel:[1,0,0]
	v_cvt_scalef32_pk_f32_fp4 v[138:139], v236, 1.0 op_sel:[0,1,0]
	v_cvt_scalef32_pk_f32_fp4 v[140:141], v236, 1.0 op_sel:[1,1,0]
	s_waitcnt lgkmcnt(0)
	v_pk_fma_f32 v[128:129], v[130:131], v[134:135], v[128:129] op_sel_hi:[0,1,1]
	v_pk_fma_f32 v[126:127], v[130:131], v[136:137], v[126:127] op_sel_hi:[0,1,1]
	v_pk_fma_f32 v[122:123], v[130:131], v[138:139], v[122:123] op_sel_hi:[0,1,1]
	v_pk_fma_f32 v[120:121], v[130:131], v[140:141], v[120:121] op_sel_hi:[0,1,1]
	v_cvt_scalef32_pk_f32_fp4 v[134:135], v237, 1.0
	v_cvt_scalef32_pk_f32_fp4 v[136:137], v237, 1.0 op_sel:[1,0,0]
	v_cvt_scalef32_pk_f32_fp4 v[138:139], v237, 1.0 op_sel:[0,1,0]
	v_cvt_scalef32_pk_f32_fp4 v[140:141], v237, 1.0 op_sel:[1,1,0]
	v_pk_fma_f32 v[118:119], v[130:131], v[134:135], v[118:119] op_sel_hi:[0,1,1]
	v_pk_fma_f32 v[116:117], v[130:131], v[136:137], v[116:117] op_sel_hi:[0,1,1]
	v_pk_fma_f32 v[114:115], v[130:131], v[138:139], v[114:115] op_sel_hi:[0,1,1]
	v_pk_fma_f32 v[112:113], v[130:131], v[140:141], v[112:113] op_sel_hi:[0,1,1]
	v_cvt_scalef32_pk_f32_fp4 v[134:135], v238, 1.0
	v_cvt_scalef32_pk_f32_fp4 v[136:137], v238, 1.0 op_sel:[1,0,0]
	v_cvt_scalef32_pk_f32_fp4 v[138:139], v238, 1.0 op_sel:[0,1,0]
	v_cvt_scalef32_pk_f32_fp4 v[140:141], v238, 1.0 op_sel:[1,1,0]
	v_pk_fma_f32 v[80:81], v[130:131], v[134:135], v[80:81] op_sel_hi:[0,1,1]
	v_pk_fma_f32 v[78:79], v[130:131], v[136:137], v[78:79] op_sel_hi:[0,1,1]
	v_pk_fma_f32 v[76:77], v[130:131], v[138:139], v[76:77] op_sel_hi:[0,1,1]
	v_pk_fma_f32 v[74:75], v[130:131], v[140:141], v[74:75] op_sel_hi:[0,1,1]
	v_cvt_scalef32_pk_f32_fp4 v[134:135], v239, 1.0
	v_cvt_scalef32_pk_f32_fp4 v[136:137], v239, 1.0 op_sel:[1,0,0]
	v_cvt_scalef32_pk_f32_fp4 v[138:139], v239, 1.0 op_sel:[0,1,0]
	v_cvt_scalef32_pk_f32_fp4 v[140:141], v239, 1.0 op_sel:[1,1,0]
	v_pk_fma_f32 v[72:73], v[130:131], v[134:135], v[72:73] op_sel_hi:[0,1,1]
	v_pk_fma_f32 v[70:71], v[130:131], v[136:137], v[70:71] op_sel_hi:[0,1,1]
	v_pk_fma_f32 v[68:69], v[130:131], v[138:139], v[68:69] op_sel_hi:[0,1,1]
	v_pk_fma_f32 v[66:67], v[130:131], v[140:141], v[66:67] op_sel_hi:[0,1,1]
	s_waitcnt vmcnt(14)
	v_cvt_scalef32_pk_f32_fp4 v[134:135], v240, 1.0
	v_cvt_scalef32_pk_f32_fp4 v[136:137], v240, 1.0 op_sel:[1,0,0]
	v_cvt_scalef32_pk_f32_fp4 v[138:139], v240, 1.0 op_sel:[0,1,0]
	v_cvt_scalef32_pk_f32_fp4 v[140:141], v240, 1.0 op_sel:[1,1,0]
	v_pk_fma_f32 v[34:35], v[130:131], v[134:135], v[34:35] op_sel_hi:[0,1,1]
	v_pk_fma_f32 v[36:37], v[130:131], v[136:137], v[36:37] op_sel_hi:[0,1,1]
	v_pk_fma_f32 v[38:39], v[130:131], v[138:139], v[38:39] op_sel_hi:[0,1,1]
	v_pk_fma_f32 v[40:41], v[130:131], v[140:141], v[40:41] op_sel_hi:[0,1,1]
	v_cvt_scalef32_pk_f32_fp4 v[134:135], v241, 1.0
	v_cvt_scalef32_pk_f32_fp4 v[136:137], v241, 1.0 op_sel:[1,0,0]
	v_cvt_scalef32_pk_f32_fp4 v[138:139], v241, 1.0 op_sel:[0,1,0]
	v_cvt_scalef32_pk_f32_fp4 v[140:141], v241, 1.0 op_sel:[1,1,0]
	v_pk_fma_f32 v[42:43], v[130:131], v[134:135], v[42:43] op_sel_hi:[0,1,1]
	v_pk_fma_f32 v[44:45], v[130:131], v[136:137], v[44:45] op_sel_hi:[0,1,1]
	v_pk_fma_f32 v[46:47], v[130:131], v[138:139], v[46:47] op_sel_hi:[0,1,1]
	v_pk_fma_f32 v[48:49], v[130:131], v[140:141], v[48:49] op_sel_hi:[0,1,1]
	v_cvt_scalef32_pk_f32_fp4 v[134:135], v242, 1.0
	v_cvt_scalef32_pk_f32_fp4 v[136:137], v242, 1.0 op_sel:[1,0,0]
	v_cvt_scalef32_pk_f32_fp4 v[138:139], v242, 1.0 op_sel:[0,1,0]
	v_cvt_scalef32_pk_f32_fp4 v[140:141], v242, 1.0 op_sel:[1,1,0]
	v_pk_fma_f32 v[50:51], v[130:131], v[134:135], v[50:51] op_sel_hi:[0,1,1]
	v_pk_fma_f32 v[52:53], v[130:131], v[136:137], v[52:53] op_sel_hi:[0,1,1]
	v_pk_fma_f32 v[54:55], v[130:131], v[138:139], v[54:55] op_sel_hi:[0,1,1]
	v_pk_fma_f32 v[56:57], v[130:131], v[140:141], v[56:57] op_sel_hi:[0,1,1]
	v_cvt_scalef32_pk_f32_fp4 v[134:135], v243, 1.0
	v_cvt_scalef32_pk_f32_fp4 v[136:137], v243, 1.0 op_sel:[1,0,0]
	v_cvt_scalef32_pk_f32_fp4 v[138:139], v243, 1.0 op_sel:[0,1,0]
	v_cvt_scalef32_pk_f32_fp4 v[140:141], v243, 1.0 op_sel:[1,1,0]
	v_pk_fma_f32 v[58:59], v[130:131], v[134:135], v[58:59] op_sel_hi:[0,1,1]
	v_pk_fma_f32 v[60:61], v[130:131], v[136:137], v[60:61] op_sel_hi:[0,1,1]
	v_pk_fma_f32 v[62:63], v[130:131], v[138:139], v[62:63] op_sel_hi:[0,1,1]
	v_pk_fma_f32 v[64:65], v[130:131], v[140:141], v[64:65] op_sel_hi:[0,1,1]
	v_mad_u64_u32 v[248:249], vcc, v227, s0, v[86:87]
	global_load_dwordx4 v[236:239], v[248:249], off
	global_load_dwordx4 v[240:243], v[248:249], off offset:256
	ds_read_b32 v250, v131 offset:112
	ds_read_b32 v130, v132 offset:112
	s_waitcnt vmcnt(15)
	v_cvt_scalef32_pk_f32_fp4 v[134:135], v244, 1.0
	v_cvt_scalef32_pk_f32_fp4 v[136:137], v244, 1.0 op_sel:[1,0,0]
	v_cvt_scalef32_pk_f32_fp4 v[138:139], v244, 1.0 op_sel:[0,1,0]
	v_cvt_scalef32_pk_f32_fp4 v[140:141], v244, 1.0 op_sel:[1,1,0]
	s_waitcnt lgkmcnt(0)
	v_pk_fma_f32 v[128:129], v[130:131], v[134:135], v[128:129] op_sel_hi:[0,1,1]
	v_pk_fma_f32 v[126:127], v[130:131], v[136:137], v[126:127] op_sel_hi:[0,1,1]
	v_pk_fma_f32 v[122:123], v[130:131], v[138:139], v[122:123] op_sel_hi:[0,1,1]
	v_pk_fma_f32 v[120:121], v[130:131], v[140:141], v[120:121] op_sel_hi:[0,1,1]
	v_cvt_scalef32_pk_f32_fp4 v[134:135], v245, 1.0
	v_cvt_scalef32_pk_f32_fp4 v[136:137], v245, 1.0 op_sel:[1,0,0]
	v_cvt_scalef32_pk_f32_fp4 v[138:139], v245, 1.0 op_sel:[0,1,0]
	v_cvt_scalef32_pk_f32_fp4 v[140:141], v245, 1.0 op_sel:[1,1,0]
	v_pk_fma_f32 v[118:119], v[130:131], v[134:135], v[118:119] op_sel_hi:[0,1,1]
	v_pk_fma_f32 v[116:117], v[130:131], v[136:137], v[116:117] op_sel_hi:[0,1,1]
	v_pk_fma_f32 v[114:115], v[130:131], v[138:139], v[114:115] op_sel_hi:[0,1,1]
	v_pk_fma_f32 v[112:113], v[130:131], v[140:141], v[112:113] op_sel_hi:[0,1,1]
	v_cvt_scalef32_pk_f32_fp4 v[134:135], v246, 1.0
	v_cvt_scalef32_pk_f32_fp4 v[136:137], v246, 1.0 op_sel:[1,0,0]
	v_cvt_scalef32_pk_f32_fp4 v[138:139], v246, 1.0 op_sel:[0,1,0]
	v_cvt_scalef32_pk_f32_fp4 v[140:141], v246, 1.0 op_sel:[1,1,0]
	v_pk_fma_f32 v[80:81], v[130:131], v[134:135], v[80:81] op_sel_hi:[0,1,1]
	v_pk_fma_f32 v[78:79], v[130:131], v[136:137], v[78:79] op_sel_hi:[0,1,1]
	v_pk_fma_f32 v[76:77], v[130:131], v[138:139], v[76:77] op_sel_hi:[0,1,1]
	v_pk_fma_f32 v[74:75], v[130:131], v[140:141], v[74:75] op_sel_hi:[0,1,1]
	v_cvt_scalef32_pk_f32_fp4 v[134:135], v247, 1.0
	v_cvt_scalef32_pk_f32_fp4 v[136:137], v247, 1.0 op_sel:[1,0,0]
	v_cvt_scalef32_pk_f32_fp4 v[138:139], v247, 1.0 op_sel:[0,1,0]
	v_cvt_scalef32_pk_f32_fp4 v[140:141], v247, 1.0 op_sel:[1,1,0]
	v_pk_fma_f32 v[72:73], v[130:131], v[134:135], v[72:73] op_sel_hi:[0,1,1]
	v_pk_fma_f32 v[70:71], v[130:131], v[136:137], v[70:71] op_sel_hi:[0,1,1]
	v_pk_fma_f32 v[68:69], v[130:131], v[138:139], v[68:69] op_sel_hi:[0,1,1]
	v_pk_fma_f32 v[66:67], v[130:131], v[140:141], v[66:67] op_sel_hi:[0,1,1]
	s_waitcnt vmcnt(14)
	v_cvt_scalef32_pk_f32_fp4 v[134:135], v228, 1.0
	v_cvt_scalef32_pk_f32_fp4 v[136:137], v228, 1.0 op_sel:[1,0,0]
	v_cvt_scalef32_pk_f32_fp4 v[138:139], v228, 1.0 op_sel:[0,1,0]
	v_cvt_scalef32_pk_f32_fp4 v[140:141], v228, 1.0 op_sel:[1,1,0]
	v_pk_fma_f32 v[34:35], v[130:131], v[134:135], v[34:35] op_sel_hi:[0,1,1]
	v_pk_fma_f32 v[36:37], v[130:131], v[136:137], v[36:37] op_sel_hi:[0,1,1]
	v_pk_fma_f32 v[38:39], v[130:131], v[138:139], v[38:39] op_sel_hi:[0,1,1]
	v_pk_fma_f32 v[40:41], v[130:131], v[140:141], v[40:41] op_sel_hi:[0,1,1]
	v_cvt_scalef32_pk_f32_fp4 v[134:135], v229, 1.0
	v_cvt_scalef32_pk_f32_fp4 v[136:137], v229, 1.0 op_sel:[1,0,0]
	v_cvt_scalef32_pk_f32_fp4 v[138:139], v229, 1.0 op_sel:[0,1,0]
	v_cvt_scalef32_pk_f32_fp4 v[140:141], v229, 1.0 op_sel:[1,1,0]
	v_pk_fma_f32 v[42:43], v[130:131], v[134:135], v[42:43] op_sel_hi:[0,1,1]
	v_pk_fma_f32 v[44:45], v[130:131], v[136:137], v[44:45] op_sel_hi:[0,1,1]
	v_pk_fma_f32 v[46:47], v[130:131], v[138:139], v[46:47] op_sel_hi:[0,1,1]
	v_pk_fma_f32 v[48:49], v[130:131], v[140:141], v[48:49] op_sel_hi:[0,1,1]
	v_cvt_scalef32_pk_f32_fp4 v[134:135], v230, 1.0
	v_cvt_scalef32_pk_f32_fp4 v[136:137], v230, 1.0 op_sel:[1,0,0]
	v_cvt_scalef32_pk_f32_fp4 v[138:139], v230, 1.0 op_sel:[0,1,0]
	v_cvt_scalef32_pk_f32_fp4 v[140:141], v230, 1.0 op_sel:[1,1,0]
	v_pk_fma_f32 v[50:51], v[130:131], v[134:135], v[50:51] op_sel_hi:[0,1,1]
	v_pk_fma_f32 v[52:53], v[130:131], v[136:137], v[52:53] op_sel_hi:[0,1,1]
	v_pk_fma_f32 v[54:55], v[130:131], v[138:139], v[54:55] op_sel_hi:[0,1,1]
	v_pk_fma_f32 v[56:57], v[130:131], v[140:141], v[56:57] op_sel_hi:[0,1,1]
	v_cvt_scalef32_pk_f32_fp4 v[134:135], v231, 1.0
	v_cvt_scalef32_pk_f32_fp4 v[136:137], v231, 1.0 op_sel:[1,0,0]
	v_cvt_scalef32_pk_f32_fp4 v[138:139], v231, 1.0 op_sel:[0,1,0]
	v_cvt_scalef32_pk_f32_fp4 v[140:141], v231, 1.0 op_sel:[1,1,0]
	v_pk_fma_f32 v[58:59], v[130:131], v[134:135], v[58:59] op_sel_hi:[0,1,1]
	v_pk_fma_f32 v[60:61], v[130:131], v[136:137], v[60:61] op_sel_hi:[0,1,1]
	v_pk_fma_f32 v[62:63], v[130:131], v[138:139], v[62:63] op_sel_hi:[0,1,1]
	v_pk_fma_f32 v[64:65], v[130:131], v[140:141], v[64:65] op_sel_hi:[0,1,1]
	v_mad_u64_u32 v[248:249], vcc, v250, s0, v[86:87]
	global_load_dwordx4 v[244:247], v[248:249], off
	global_load_dwordx4 v[228:231], v[248:249], off offset:256
	ds_read_b32 v227, v131 offset:128
	ds_read_b32 v130, v132 offset:128
	s_waitcnt vmcnt(15)
	v_cvt_scalef32_pk_f32_fp4 v[134:135], v10, 1.0
	v_cvt_scalef32_pk_f32_fp4 v[136:137], v10, 1.0 op_sel:[1,0,0]
	v_cvt_scalef32_pk_f32_fp4 v[138:139], v10, 1.0 op_sel:[0,1,0]
	v_cvt_scalef32_pk_f32_fp4 v[140:141], v10, 1.0 op_sel:[1,1,0]
	s_waitcnt lgkmcnt(0)
	v_pk_fma_f32 v[128:129], v[130:131], v[134:135], v[128:129] op_sel_hi:[0,1,1]
	v_pk_fma_f32 v[126:127], v[130:131], v[136:137], v[126:127] op_sel_hi:[0,1,1]
	v_pk_fma_f32 v[122:123], v[130:131], v[138:139], v[122:123] op_sel_hi:[0,1,1]
	v_pk_fma_f32 v[120:121], v[130:131], v[140:141], v[120:121] op_sel_hi:[0,1,1]
	v_cvt_scalef32_pk_f32_fp4 v[134:135], v11, 1.0
	v_cvt_scalef32_pk_f32_fp4 v[136:137], v11, 1.0 op_sel:[1,0,0]
	v_cvt_scalef32_pk_f32_fp4 v[138:139], v11, 1.0 op_sel:[0,1,0]
	v_cvt_scalef32_pk_f32_fp4 v[140:141], v11, 1.0 op_sel:[1,1,0]
	v_pk_fma_f32 v[118:119], v[130:131], v[134:135], v[118:119] op_sel_hi:[0,1,1]
	v_pk_fma_f32 v[116:117], v[130:131], v[136:137], v[116:117] op_sel_hi:[0,1,1]
	v_pk_fma_f32 v[114:115], v[130:131], v[138:139], v[114:115] op_sel_hi:[0,1,1]
	v_pk_fma_f32 v[112:113], v[130:131], v[140:141], v[112:113] op_sel_hi:[0,1,1]
	v_cvt_scalef32_pk_f32_fp4 v[134:135], v12, 1.0
	v_cvt_scalef32_pk_f32_fp4 v[136:137], v12, 1.0 op_sel:[1,0,0]
	v_cvt_scalef32_pk_f32_fp4 v[138:139], v12, 1.0 op_sel:[0,1,0]
	v_cvt_scalef32_pk_f32_fp4 v[140:141], v12, 1.0 op_sel:[1,1,0]
	v_pk_fma_f32 v[80:81], v[130:131], v[134:135], v[80:81] op_sel_hi:[0,1,1]
	v_pk_fma_f32 v[78:79], v[130:131], v[136:137], v[78:79] op_sel_hi:[0,1,1]
	v_pk_fma_f32 v[76:77], v[130:131], v[138:139], v[76:77] op_sel_hi:[0,1,1]
	v_pk_fma_f32 v[74:75], v[130:131], v[140:141], v[74:75] op_sel_hi:[0,1,1]
	v_cvt_scalef32_pk_f32_fp4 v[134:135], v13, 1.0
	v_cvt_scalef32_pk_f32_fp4 v[136:137], v13, 1.0 op_sel:[1,0,0]
	v_cvt_scalef32_pk_f32_fp4 v[138:139], v13, 1.0 op_sel:[0,1,0]
	v_cvt_scalef32_pk_f32_fp4 v[140:141], v13, 1.0 op_sel:[1,1,0]
	v_pk_fma_f32 v[72:73], v[130:131], v[134:135], v[72:73] op_sel_hi:[0,1,1]
	v_pk_fma_f32 v[70:71], v[130:131], v[136:137], v[70:71] op_sel_hi:[0,1,1]
	v_pk_fma_f32 v[68:69], v[130:131], v[138:139], v[68:69] op_sel_hi:[0,1,1]
	v_pk_fma_f32 v[66:67], v[130:131], v[140:141], v[66:67] op_sel_hi:[0,1,1]
	s_waitcnt vmcnt(14)
	v_cvt_scalef32_pk_f32_fp4 v[134:135], v2, 1.0
	v_cvt_scalef32_pk_f32_fp4 v[136:137], v2, 1.0 op_sel:[1,0,0]
	v_cvt_scalef32_pk_f32_fp4 v[138:139], v2, 1.0 op_sel:[0,1,0]
	v_cvt_scalef32_pk_f32_fp4 v[140:141], v2, 1.0 op_sel:[1,1,0]
	v_pk_fma_f32 v[34:35], v[130:131], v[134:135], v[34:35] op_sel_hi:[0,1,1]
	v_pk_fma_f32 v[36:37], v[130:131], v[136:137], v[36:37] op_sel_hi:[0,1,1]
	v_pk_fma_f32 v[38:39], v[130:131], v[138:139], v[38:39] op_sel_hi:[0,1,1]
	v_pk_fma_f32 v[40:41], v[130:131], v[140:141], v[40:41] op_sel_hi:[0,1,1]
	v_cvt_scalef32_pk_f32_fp4 v[134:135], v3, 1.0
	v_cvt_scalef32_pk_f32_fp4 v[136:137], v3, 1.0 op_sel:[1,0,0]
	v_cvt_scalef32_pk_f32_fp4 v[138:139], v3, 1.0 op_sel:[0,1,0]
	v_cvt_scalef32_pk_f32_fp4 v[140:141], v3, 1.0 op_sel:[1,1,0]
	v_pk_fma_f32 v[42:43], v[130:131], v[134:135], v[42:43] op_sel_hi:[0,1,1]
	v_pk_fma_f32 v[44:45], v[130:131], v[136:137], v[44:45] op_sel_hi:[0,1,1]
	v_pk_fma_f32 v[46:47], v[130:131], v[138:139], v[46:47] op_sel_hi:[0,1,1]
	v_pk_fma_f32 v[48:49], v[130:131], v[140:141], v[48:49] op_sel_hi:[0,1,1]
	v_cvt_scalef32_pk_f32_fp4 v[134:135], v4, 1.0
	v_cvt_scalef32_pk_f32_fp4 v[136:137], v4, 1.0 op_sel:[1,0,0]
	v_cvt_scalef32_pk_f32_fp4 v[138:139], v4, 1.0 op_sel:[0,1,0]
	v_cvt_scalef32_pk_f32_fp4 v[140:141], v4, 1.0 op_sel:[1,1,0]
	v_pk_fma_f32 v[50:51], v[130:131], v[134:135], v[50:51] op_sel_hi:[0,1,1]
	v_pk_fma_f32 v[52:53], v[130:131], v[136:137], v[52:53] op_sel_hi:[0,1,1]
	v_pk_fma_f32 v[54:55], v[130:131], v[138:139], v[54:55] op_sel_hi:[0,1,1]
	v_pk_fma_f32 v[56:57], v[130:131], v[140:141], v[56:57] op_sel_hi:[0,1,1]
	v_cvt_scalef32_pk_f32_fp4 v[134:135], v5, 1.0
	v_cvt_scalef32_pk_f32_fp4 v[136:137], v5, 1.0 op_sel:[1,0,0]
	v_cvt_scalef32_pk_f32_fp4 v[138:139], v5, 1.0 op_sel:[0,1,0]
	v_cvt_scalef32_pk_f32_fp4 v[140:141], v5, 1.0 op_sel:[1,1,0]
	v_pk_fma_f32 v[58:59], v[130:131], v[134:135], v[58:59] op_sel_hi:[0,1,1]
	v_pk_fma_f32 v[60:61], v[130:131], v[136:137], v[60:61] op_sel_hi:[0,1,1]
	v_pk_fma_f32 v[62:63], v[130:131], v[138:139], v[62:63] op_sel_hi:[0,1,1]
	v_pk_fma_f32 v[64:65], v[130:131], v[140:141], v[64:65] op_sel_hi:[0,1,1]
	s_add_i32 s2, s2, 8
	v_add_u32_e32 v131, 0x80, v131
	v_add_u32_e32 v132, 0x80, v132
	s_cmp_lt_u32 s2, 24
	s_cbranch_scc1 .Lpv_loop
	ds_read_b32 v130, v132 offset:16
	s_waitcnt vmcnt(13)
	v_cvt_scalef32_pk_f32_fp4 v[134:135], v14, 1.0
	v_cvt_scalef32_pk_f32_fp4 v[136:137], v14, 1.0 op_sel:[1,0,0]
	v_cvt_scalef32_pk_f32_fp4 v[138:139], v14, 1.0 op_sel:[0,1,0]
	v_cvt_scalef32_pk_f32_fp4 v[140:141], v14, 1.0 op_sel:[1,1,0]
	s_waitcnt lgkmcnt(0)
	v_pk_fma_f32 v[128:129], v[130:131], v[134:135], v[128:129] op_sel_hi:[0,1,1]
	v_pk_fma_f32 v[126:127], v[130:131], v[136:137], v[126:127] op_sel_hi:[0,1,1]
	v_pk_fma_f32 v[122:123], v[130:131], v[138:139], v[122:123] op_sel_hi:[0,1,1]
	v_pk_fma_f32 v[120:121], v[130:131], v[140:141], v[120:121] op_sel_hi:[0,1,1]
	v_cvt_scalef32_pk_f32_fp4 v[134:135], v15, 1.0
	v_cvt_scalef32_pk_f32_fp4 v[136:137], v15, 1.0 op_sel:[1,0,0]
	v_cvt_scalef32_pk_f32_fp4 v[138:139], v15, 1.0 op_sel:[0,1,0]
	v_cvt_scalef32_pk_f32_fp4 v[140:141], v15, 1.0 op_sel:[1,1,0]
	v_pk_fma_f32 v[118:119], v[130:131], v[134:135], v[118:119] op_sel_hi:[0,1,1]
	v_pk_fma_f32 v[116:117], v[130:131], v[136:137], v[116:117] op_sel_hi:[0,1,1]
	v_pk_fma_f32 v[114:115], v[130:131], v[138:139], v[114:115] op_sel_hi:[0,1,1]
	v_pk_fma_f32 v[112:113], v[130:131], v[140:141], v[112:113] op_sel_hi:[0,1,1]
	v_cvt_scalef32_pk_f32_fp4 v[134:135], v16, 1.0
	v_cvt_scalef32_pk_f32_fp4 v[136:137], v16, 1.0 op_sel:[1,0,0]
	v_cvt_scalef32_pk_f32_fp4 v[138:139], v16, 1.0 op_sel:[0,1,0]
	v_cvt_scalef32_pk_f32_fp4 v[140:141], v16, 1.0 op_sel:[1,1,0]
	v_pk_fma_f32 v[80:81], v[130:131], v[134:135], v[80:81] op_sel_hi:[0,1,1]
	v_pk_fma_f32 v[78:79], v[130:131], v[136:137], v[78:79] op_sel_hi:[0,1,1]
	v_pk_fma_f32 v[76:77], v[130:131], v[138:139], v[76:77] op_sel_hi:[0,1,1]
	v_pk_fma_f32 v[74:75], v[130:131], v[140:141], v[74:75] op_sel_hi:[0,1,1]
	v_cvt_scalef32_pk_f32_fp4 v[134:135], v17, 1.0
	v_cvt_scalef32_pk_f32_fp4 v[136:137], v17, 1.0 op_sel:[1,0,0]
	v_cvt_scalef32_pk_f32_fp4 v[138:139], v17, 1.0 op_sel:[0,1,0]
	v_cvt_scalef32_pk_f32_fp4 v[140:141], v17, 1.0 op_sel:[1,1,0]
	v_pk_fma_f32 v[72:73], v[130:131], v[134:135], v[72:73] op_sel_hi:[0,1,1]
	v_pk_fma_f32 v[70:71], v[130:131], v[136:137], v[70:71] op_sel_hi:[0,1,1]
	v_pk_fma_f32 v[68:69], v[130:131], v[138:139], v[68:69] op_sel_hi:[0,1,1]
	v_pk_fma_f32 v[66:67], v[130:131], v[140:141], v[66:67] op_sel_hi:[0,1,1]
	s_waitcnt vmcnt(12)
	v_cvt_scalef32_pk_f32_fp4 v[134:135], v6, 1.0
	v_cvt_scalef32_pk_f32_fp4 v[136:137], v6, 1.0 op_sel:[1,0,0]
	v_cvt_scalef32_pk_f32_fp4 v[138:139], v6, 1.0 op_sel:[0,1,0]
	v_cvt_scalef32_pk_f32_fp4 v[140:141], v6, 1.0 op_sel:[1,1,0]
	v_pk_fma_f32 v[34:35], v[130:131], v[134:135], v[34:35] op_sel_hi:[0,1,1]
	v_pk_fma_f32 v[36:37], v[130:131], v[136:137], v[36:37] op_sel_hi:[0,1,1]
	v_pk_fma_f32 v[38:39], v[130:131], v[138:139], v[38:39] op_sel_hi:[0,1,1]
	v_pk_fma_f32 v[40:41], v[130:131], v[140:141], v[40:41] op_sel_hi:[0,1,1]
	v_cvt_scalef32_pk_f32_fp4 v[134:135], v7, 1.0
	v_cvt_scalef32_pk_f32_fp4 v[136:137], v7, 1.0 op_sel:[1,0,0]
	v_cvt_scalef32_pk_f32_fp4 v[138:139], v7, 1.0 op_sel:[0,1,0]
	v_cvt_scalef32_pk_f32_fp4 v[140:141], v7, 1.0 op_sel:[1,1,0]
	v_pk_fma_f32 v[42:43], v[130:131], v[134:135], v[42:43] op_sel_hi:[0,1,1]
	v_pk_fma_f32 v[44:45], v[130:131], v[136:137], v[44:45] op_sel_hi:[0,1,1]
	v_pk_fma_f32 v[46:47], v[130:131], v[138:139], v[46:47] op_sel_hi:[0,1,1]
	v_pk_fma_f32 v[48:49], v[130:131], v[140:141], v[48:49] op_sel_hi:[0,1,1]
	v_cvt_scalef32_pk_f32_fp4 v[134:135], v8, 1.0
	v_cvt_scalef32_pk_f32_fp4 v[136:137], v8, 1.0 op_sel:[1,0,0]
	v_cvt_scalef32_pk_f32_fp4 v[138:139], v8, 1.0 op_sel:[0,1,0]
	v_cvt_scalef32_pk_f32_fp4 v[140:141], v8, 1.0 op_sel:[1,1,0]
	v_pk_fma_f32 v[50:51], v[130:131], v[134:135], v[50:51] op_sel_hi:[0,1,1]
	v_pk_fma_f32 v[52:53], v[130:131], v[136:137], v[52:53] op_sel_hi:[0,1,1]
	v_pk_fma_f32 v[54:55], v[130:131], v[138:139], v[54:55] op_sel_hi:[0,1,1]
	v_pk_fma_f32 v[56:57], v[130:131], v[140:141], v[56:57] op_sel_hi:[0,1,1]
	v_cvt_scalef32_pk_f32_fp4 v[134:135], v9, 1.0
	v_cvt_scalef32_pk_f32_fp4 v[136:137], v9, 1.0 op_sel:[1,0,0]
	v_cvt_scalef32_pk_f32_fp4 v[138:139], v9, 1.0 op_sel:[0,1,0]
	v_cvt_scalef32_pk_f32_fp4 v[140:141], v9, 1.0 op_sel:[1,1,0]
	v_pk_fma_f32 v[58:59], v[130:131], v[134:135], v[58:59] op_sel_hi:[0,1,1]
	v_pk_fma_f32 v[60:61], v[130:131], v[136:137], v[60:61] op_sel_hi:[0,1,1]
	v_pk_fma_f32 v[62:63], v[130:131], v[138:139], v[62:63] op_sel_hi:[0,1,1]
	v_pk_fma_f32 v[64:65], v[130:131], v[140:141], v[64:65] op_sel_hi:[0,1,1]
	ds_read_b32 v130, v132 offset:32
	s_waitcnt vmcnt(11)
	v_cvt_scalef32_pk_f32_fp4 v[134:135], v22, 1.0
	v_cvt_scalef32_pk_f32_fp4 v[136:137], v22, 1.0 op_sel:[1,0,0]
	v_cvt_scalef32_pk_f32_fp4 v[138:139], v22, 1.0 op_sel:[0,1,0]
	v_cvt_scalef32_pk_f32_fp4 v[140:141], v22, 1.0 op_sel:[1,1,0]
	s_waitcnt lgkmcnt(0)
	v_pk_fma_f32 v[128:129], v[130:131], v[134:135], v[128:129] op_sel_hi:[0,1,1]
	v_pk_fma_f32 v[126:127], v[130:131], v[136:137], v[126:127] op_sel_hi:[0,1,1]
	v_pk_fma_f32 v[122:123], v[130:131], v[138:139], v[122:123] op_sel_hi:[0,1,1]
	v_pk_fma_f32 v[120:121], v[130:131], v[140:141], v[120:121] op_sel_hi:[0,1,1]
	v_cvt_scalef32_pk_f32_fp4 v[134:135], v23, 1.0
	v_cvt_scalef32_pk_f32_fp4 v[136:137], v23, 1.0 op_sel:[1,0,0]
	v_cvt_scalef32_pk_f32_fp4 v[138:139], v23, 1.0 op_sel:[0,1,0]
	v_cvt_scalef32_pk_f32_fp4 v[140:141], v23, 1.0 op_sel:[1,1,0]
	v_pk_fma_f32 v[118:119], v[130:131], v[134:135], v[118:119] op_sel_hi:[0,1,1]
	v_pk_fma_f32 v[116:117], v[130:131], v[136:137], v[116:117] op_sel_hi:[0,1,1]
	v_pk_fma_f32 v[114:115], v[130:131], v[138:139], v[114:115] op_sel_hi:[0,1,1]
	v_pk_fma_f32 v[112:113], v[130:131], v[140:141], v[112:113] op_sel_hi:[0,1,1]
	v_cvt_scalef32_pk_f32_fp4 v[134:135], v24, 1.0
	v_cvt_scalef32_pk_f32_fp4 v[136:137], v24, 1.0 op_sel:[1,0,0]
	v_cvt_scalef32_pk_f32_fp4 v[138:139], v24, 1.0 op_sel:[0,1,0]
	v_cvt_scalef32_pk_f32_fp4 v[140:141], v24, 1.0 op_sel:[1,1,0]
	v_pk_fma_f32 v[80:81], v[130:131], v[134:135], v[80:81] op_sel_hi:[0,1,1]
	v_pk_fma_f32 v[78:79], v[130:131], v[136:137], v[78:79] op_sel_hi:[0,1,1]
	v_pk_fma_f32 v[76:77], v[130:131], v[138:139], v[76:77] op_sel_hi:[0,1,1]
	v_pk_fma_f32 v[74:75], v[130:131], v[140:141], v[74:75] op_sel_hi:[0,1,1]
	v_cvt_scalef32_pk_f32_fp4 v[134:135], v25, 1.0
	v_cvt_scalef32_pk_f32_fp4 v[136:137], v25, 1.0 op_sel:[1,0,0]
	v_cvt_scalef32_pk_f32_fp4 v[138:139], v25, 1.0 op_sel:[0,1,0]
	v_cvt_scalef32_pk_f32_fp4 v[140:141], v25, 1.0 op_sel:[1,1,0]
	v_pk_fma_f32 v[72:73], v[130:131], v[134:135], v[72:73] op_sel_hi:[0,1,1]
	v_pk_fma_f32 v[70:71], v[130:131], v[136:137], v[70:71] op_sel_hi:[0,1,1]
	v_pk_fma_f32 v[68:69], v[130:131], v[138:139], v[68:69] op_sel_hi:[0,1,1]
	v_pk_fma_f32 v[66:67], v[130:131], v[140:141], v[66:67] op_sel_hi:[0,1,1]
	s_waitcnt vmcnt(10)
	v_cvt_scalef32_pk_f32_fp4 v[134:135], v18, 1.0
	v_cvt_scalef32_pk_f32_fp4 v[136:137], v18, 1.0 op_sel:[1,0,0]
	v_cvt_scalef32_pk_f32_fp4 v[138:139], v18, 1.0 op_sel:[0,1,0]
	v_cvt_scalef32_pk_f32_fp4 v[140:141], v18, 1.0 op_sel:[1,1,0]
	v_pk_fma_f32 v[34:35], v[130:131], v[134:135], v[34:35] op_sel_hi:[0,1,1]
	v_pk_fma_f32 v[36:37], v[130:131], v[136:137], v[36:37] op_sel_hi:[0,1,1]
	v_pk_fma_f32 v[38:39], v[130:131], v[138:139], v[38:39] op_sel_hi:[0,1,1]
	v_pk_fma_f32 v[40:41], v[130:131], v[140:141], v[40:41] op_sel_hi:[0,1,1]
	v_cvt_scalef32_pk_f32_fp4 v[134:135], v19, 1.0
	v_cvt_scalef32_pk_f32_fp4 v[136:137], v19, 1.0 op_sel:[1,0,0]
	v_cvt_scalef32_pk_f32_fp4 v[138:139], v19, 1.0 op_sel:[0,1,0]
	v_cvt_scalef32_pk_f32_fp4 v[140:141], v19, 1.0 op_sel:[1,1,0]
	v_pk_fma_f32 v[42:43], v[130:131], v[134:135], v[42:43] op_sel_hi:[0,1,1]
	v_pk_fma_f32 v[44:45], v[130:131], v[136:137], v[44:45] op_sel_hi:[0,1,1]
	v_pk_fma_f32 v[46:47], v[130:131], v[138:139], v[46:47] op_sel_hi:[0,1,1]
	v_pk_fma_f32 v[48:49], v[130:131], v[140:141], v[48:49] op_sel_hi:[0,1,1]
	v_cvt_scalef32_pk_f32_fp4 v[134:135], v20, 1.0
	v_cvt_scalef32_pk_f32_fp4 v[136:137], v20, 1.0 op_sel:[1,0,0]
	v_cvt_scalef32_pk_f32_fp4 v[138:139], v20, 1.0 op_sel:[0,1,0]
	v_cvt_scalef32_pk_f32_fp4 v[140:141], v20, 1.0 op_sel:[1,1,0]
	v_pk_fma_f32 v[50:51], v[130:131], v[134:135], v[50:51] op_sel_hi:[0,1,1]
	v_pk_fma_f32 v[52:53], v[130:131], v[136:137], v[52:53] op_sel_hi:[0,1,1]
	v_pk_fma_f32 v[54:55], v[130:131], v[138:139], v[54:55] op_sel_hi:[0,1,1]
	v_pk_fma_f32 v[56:57], v[130:131], v[140:141], v[56:57] op_sel_hi:[0,1,1]
	v_cvt_scalef32_pk_f32_fp4 v[134:135], v21, 1.0
	v_cvt_scalef32_pk_f32_fp4 v[136:137], v21, 1.0 op_sel:[1,0,0]
	v_cvt_scalef32_pk_f32_fp4 v[138:139], v21, 1.0 op_sel:[0,1,0]
	v_cvt_scalef32_pk_f32_fp4 v[140:141], v21, 1.0 op_sel:[1,1,0]
	v_pk_fma_f32 v[58:59], v[130:131], v[134:135], v[58:59] op_sel_hi:[0,1,1]
	v_pk_fma_f32 v[60:61], v[130:131], v[136:137], v[60:61] op_sel_hi:[0,1,1]
	v_pk_fma_f32 v[62:63], v[130:131], v[138:139], v[62:63] op_sel_hi:[0,1,1]
	v_pk_fma_f32 v[64:65], v[130:131], v[140:141], v[64:65] op_sel_hi:[0,1,1]
	ds_read_b32 v130, v132 offset:48
	s_waitcnt vmcnt(9)
	v_cvt_scalef32_pk_f32_fp4 v[134:135], v30, 1.0
	v_cvt_scalef32_pk_f32_fp4 v[136:137], v30, 1.0 op_sel:[1,0,0]
	v_cvt_scalef32_pk_f32_fp4 v[138:139], v30, 1.0 op_sel:[0,1,0]
	v_cvt_scalef32_pk_f32_fp4 v[140:141], v30, 1.0 op_sel:[1,1,0]
	s_waitcnt lgkmcnt(0)
	v_pk_fma_f32 v[128:129], v[130:131], v[134:135], v[128:129] op_sel_hi:[0,1,1]
	v_pk_fma_f32 v[126:127], v[130:131], v[136:137], v[126:127] op_sel_hi:[0,1,1]
	v_pk_fma_f32 v[122:123], v[130:131], v[138:139], v[122:123] op_sel_hi:[0,1,1]
	v_pk_fma_f32 v[120:121], v[130:131], v[140:141], v[120:121] op_sel_hi:[0,1,1]
	v_cvt_scalef32_pk_f32_fp4 v[134:135], v31, 1.0
	v_cvt_scalef32_pk_f32_fp4 v[136:137], v31, 1.0 op_sel:[1,0,0]
	v_cvt_scalef32_pk_f32_fp4 v[138:139], v31, 1.0 op_sel:[0,1,0]
	v_cvt_scalef32_pk_f32_fp4 v[140:141], v31, 1.0 op_sel:[1,1,0]
	v_pk_fma_f32 v[118:119], v[130:131], v[134:135], v[118:119] op_sel_hi:[0,1,1]
	v_pk_fma_f32 v[116:117], v[130:131], v[136:137], v[116:117] op_sel_hi:[0,1,1]
	v_pk_fma_f32 v[114:115], v[130:131], v[138:139], v[114:115] op_sel_hi:[0,1,1]
	v_pk_fma_f32 v[112:113], v[130:131], v[140:141], v[112:113] op_sel_hi:[0,1,1]
	v_cvt_scalef32_pk_f32_fp4 v[134:135], v32, 1.0
	v_cvt_scalef32_pk_f32_fp4 v[136:137], v32, 1.0 op_sel:[1,0,0]
	v_cvt_scalef32_pk_f32_fp4 v[138:139], v32, 1.0 op_sel:[0,1,0]
	v_cvt_scalef32_pk_f32_fp4 v[140:141], v32, 1.0 op_sel:[1,1,0]
	v_pk_fma_f32 v[80:81], v[130:131], v[134:135], v[80:81] op_sel_hi:[0,1,1]
	v_pk_fma_f32 v[78:79], v[130:131], v[136:137], v[78:79] op_sel_hi:[0,1,1]
	v_pk_fma_f32 v[76:77], v[130:131], v[138:139], v[76:77] op_sel_hi:[0,1,1]
	v_pk_fma_f32 v[74:75], v[130:131], v[140:141], v[74:75] op_sel_hi:[0,1,1]
	v_cvt_scalef32_pk_f32_fp4 v[134:135], v33, 1.0
	v_cvt_scalef32_pk_f32_fp4 v[136:137], v33, 1.0 op_sel:[1,0,0]
	v_cvt_scalef32_pk_f32_fp4 v[138:139], v33, 1.0 op_sel:[0,1,0]
	v_cvt_scalef32_pk_f32_fp4 v[140:141], v33, 1.0 op_sel:[1,1,0]
	v_pk_fma_f32 v[72:73], v[130:131], v[134:135], v[72:73] op_sel_hi:[0,1,1]
	v_pk_fma_f32 v[70:71], v[130:131], v[136:137], v[70:71] op_sel_hi:[0,1,1]
	v_pk_fma_f32 v[68:69], v[130:131], v[138:139], v[68:69] op_sel_hi:[0,1,1]
	v_pk_fma_f32 v[66:67], v[130:131], v[140:141], v[66:67] op_sel_hi:[0,1,1]
	s_waitcnt vmcnt(8)
	v_cvt_scalef32_pk_f32_fp4 v[134:135], v26, 1.0
	v_cvt_scalef32_pk_f32_fp4 v[136:137], v26, 1.0 op_sel:[1,0,0]
	v_cvt_scalef32_pk_f32_fp4 v[138:139], v26, 1.0 op_sel:[0,1,0]
	v_cvt_scalef32_pk_f32_fp4 v[140:141], v26, 1.0 op_sel:[1,1,0]
	v_pk_fma_f32 v[34:35], v[130:131], v[134:135], v[34:35] op_sel_hi:[0,1,1]
	v_pk_fma_f32 v[36:37], v[130:131], v[136:137], v[36:37] op_sel_hi:[0,1,1]
	v_pk_fma_f32 v[38:39], v[130:131], v[138:139], v[38:39] op_sel_hi:[0,1,1]
	v_pk_fma_f32 v[40:41], v[130:131], v[140:141], v[40:41] op_sel_hi:[0,1,1]
	v_cvt_scalef32_pk_f32_fp4 v[134:135], v27, 1.0
	v_cvt_scalef32_pk_f32_fp4 v[136:137], v27, 1.0 op_sel:[1,0,0]
	v_cvt_scalef32_pk_f32_fp4 v[138:139], v27, 1.0 op_sel:[0,1,0]
	v_cvt_scalef32_pk_f32_fp4 v[140:141], v27, 1.0 op_sel:[1,1,0]
	v_pk_fma_f32 v[42:43], v[130:131], v[134:135], v[42:43] op_sel_hi:[0,1,1]
	v_pk_fma_f32 v[44:45], v[130:131], v[136:137], v[44:45] op_sel_hi:[0,1,1]
	v_pk_fma_f32 v[46:47], v[130:131], v[138:139], v[46:47] op_sel_hi:[0,1,1]
	v_pk_fma_f32 v[48:49], v[130:131], v[140:141], v[48:49] op_sel_hi:[0,1,1]
	v_cvt_scalef32_pk_f32_fp4 v[134:135], v28, 1.0
	v_cvt_scalef32_pk_f32_fp4 v[136:137], v28, 1.0 op_sel:[1,0,0]
	v_cvt_scalef32_pk_f32_fp4 v[138:139], v28, 1.0 op_sel:[0,1,0]
	v_cvt_scalef32_pk_f32_fp4 v[140:141], v28, 1.0 op_sel:[1,1,0]
	v_pk_fma_f32 v[50:51], v[130:131], v[134:135], v[50:51] op_sel_hi:[0,1,1]
	v_pk_fma_f32 v[52:53], v[130:131], v[136:137], v[52:53] op_sel_hi:[0,1,1]
	v_pk_fma_f32 v[54:55], v[130:131], v[138:139], v[54:55] op_sel_hi:[0,1,1]
	v_pk_fma_f32 v[56:57], v[130:131], v[140:141], v[56:57] op_sel_hi:[0,1,1]
	v_cvt_scalef32_pk_f32_fp4 v[134:135], v29, 1.0
	v_cvt_scalef32_pk_f32_fp4 v[136:137], v29, 1.0 op_sel:[1,0,0]
	v_cvt_scalef32_pk_f32_fp4 v[138:139], v29, 1.0 op_sel:[0,1,0]
	v_cvt_scalef32_pk_f32_fp4 v[140:141], v29, 1.0 op_sel:[1,1,0]
	v_pk_fma_f32 v[58:59], v[130:131], v[134:135], v[58:59] op_sel_hi:[0,1,1]
	v_pk_fma_f32 v[60:61], v[130:131], v[136:137], v[60:61] op_sel_hi:[0,1,1]
	v_pk_fma_f32 v[62:63], v[130:131], v[138:139], v[62:63] op_sel_hi:[0,1,1]
	v_pk_fma_f32 v[64:65], v[130:131], v[140:141], v[64:65] op_sel_hi:[0,1,1]
	ds_read_b32 v130, v132 offset:64
	s_waitcnt vmcnt(7)
	v_cvt_scalef32_pk_f32_fp4 v[134:135], v142, 1.0
	v_cvt_scalef32_pk_f32_fp4 v[136:137], v142, 1.0 op_sel:[1,0,0]
	v_cvt_scalef32_pk_f32_fp4 v[138:139], v142, 1.0 op_sel:[0,1,0]
	v_cvt_scalef32_pk_f32_fp4 v[140:141], v142, 1.0 op_sel:[1,1,0]
	s_waitcnt lgkmcnt(0)
	v_pk_fma_f32 v[128:129], v[130:131], v[134:135], v[128:129] op_sel_hi:[0,1,1]
	v_pk_fma_f32 v[126:127], v[130:131], v[136:137], v[126:127] op_sel_hi:[0,1,1]
	v_pk_fma_f32 v[122:123], v[130:131], v[138:139], v[122:123] op_sel_hi:[0,1,1]
	v_pk_fma_f32 v[120:121], v[130:131], v[140:141], v[120:121] op_sel_hi:[0,1,1]
	v_cvt_scalef32_pk_f32_fp4 v[134:135], v143, 1.0
	v_cvt_scalef32_pk_f32_fp4 v[136:137], v143, 1.0 op_sel:[1,0,0]
	v_cvt_scalef32_pk_f32_fp4 v[138:139], v143, 1.0 op_sel:[0,1,0]
	v_cvt_scalef32_pk_f32_fp4 v[140:141], v143, 1.0 op_sel:[1,1,0]
	v_pk_fma_f32 v[118:119], v[130:131], v[134:135], v[118:119] op_sel_hi:[0,1,1]
	v_pk_fma_f32 v[116:117], v[130:131], v[136:137], v[116:117] op_sel_hi:[0,1,1]
	v_pk_fma_f32 v[114:115], v[130:131], v[138:139], v[114:115] op_sel_hi:[0,1,1]
	v_pk_fma_f32 v[112:113], v[130:131], v[140:141], v[112:113] op_sel_hi:[0,1,1]
	v_cvt_scalef32_pk_f32_fp4 v[134:135], v144, 1.0
	v_cvt_scalef32_pk_f32_fp4 v[136:137], v144, 1.0 op_sel:[1,0,0]
	v_cvt_scalef32_pk_f32_fp4 v[138:139], v144, 1.0 op_sel:[0,1,0]
	v_cvt_scalef32_pk_f32_fp4 v[140:141], v144, 1.0 op_sel:[1,1,0]
	v_pk_fma_f32 v[80:81], v[130:131], v[134:135], v[80:81] op_sel_hi:[0,1,1]
	v_pk_fma_f32 v[78:79], v[130:131], v[136:137], v[78:79] op_sel_hi:[0,1,1]
	v_pk_fma_f32 v[76:77], v[130:131], v[138:139], v[76:77] op_sel_hi:[0,1,1]
	v_pk_fma_f32 v[74:75], v[130:131], v[140:141], v[74:75] op_sel_hi:[0,1,1]
	v_cvt_scalef32_pk_f32_fp4 v[134:135], v145, 1.0
	v_cvt_scalef32_pk_f32_fp4 v[136:137], v145, 1.0 op_sel:[1,0,0]
	v_cvt_scalef32_pk_f32_fp4 v[138:139], v145, 1.0 op_sel:[0,1,0]
	v_cvt_scalef32_pk_f32_fp4 v[140:141], v145, 1.0 op_sel:[1,1,0]
	v_pk_fma_f32 v[72:73], v[130:131], v[134:135], v[72:73] op_sel_hi:[0,1,1]
	v_pk_fma_f32 v[70:71], v[130:131], v[136:137], v[70:71] op_sel_hi:[0,1,1]
	v_pk_fma_f32 v[68:69], v[130:131], v[138:139], v[68:69] op_sel_hi:[0,1,1]
	v_pk_fma_f32 v[66:67], v[130:131], v[140:141], v[66:67] op_sel_hi:[0,1,1]
	s_waitcnt vmcnt(6)
	v_cvt_scalef32_pk_f32_fp4 v[134:135], v146, 1.0
	v_cvt_scalef32_pk_f32_fp4 v[136:137], v146, 1.0 op_sel:[1,0,0]
	v_cvt_scalef32_pk_f32_fp4 v[138:139], v146, 1.0 op_sel:[0,1,0]
	v_cvt_scalef32_pk_f32_fp4 v[140:141], v146, 1.0 op_sel:[1,1,0]
	v_pk_fma_f32 v[34:35], v[130:131], v[134:135], v[34:35] op_sel_hi:[0,1,1]
	v_pk_fma_f32 v[36:37], v[130:131], v[136:137], v[36:37] op_sel_hi:[0,1,1]
	v_pk_fma_f32 v[38:39], v[130:131], v[138:139], v[38:39] op_sel_hi:[0,1,1]
	v_pk_fma_f32 v[40:41], v[130:131], v[140:141], v[40:41] op_sel_hi:[0,1,1]
	v_cvt_scalef32_pk_f32_fp4 v[134:135], v147, 1.0
	v_cvt_scalef32_pk_f32_fp4 v[136:137], v147, 1.0 op_sel:[1,0,0]
	v_cvt_scalef32_pk_f32_fp4 v[138:139], v147, 1.0 op_sel:[0,1,0]
	v_cvt_scalef32_pk_f32_fp4 v[140:141], v147, 1.0 op_sel:[1,1,0]
	v_pk_fma_f32 v[42:43], v[130:131], v[134:135], v[42:43] op_sel_hi:[0,1,1]
	v_pk_fma_f32 v[44:45], v[130:131], v[136:137], v[44:45] op_sel_hi:[0,1,1]
	v_pk_fma_f32 v[46:47], v[130:131], v[138:139], v[46:47] op_sel_hi:[0,1,1]
	v_pk_fma_f32 v[48:49], v[130:131], v[140:141], v[48:49] op_sel_hi:[0,1,1]
	v_cvt_scalef32_pk_f32_fp4 v[134:135], v148, 1.0
	v_cvt_scalef32_pk_f32_fp4 v[136:137], v148, 1.0 op_sel:[1,0,0]
	v_cvt_scalef32_pk_f32_fp4 v[138:139], v148, 1.0 op_sel:[0,1,0]
	v_cvt_scalef32_pk_f32_fp4 v[140:141], v148, 1.0 op_sel:[1,1,0]
	v_pk_fma_f32 v[50:51], v[130:131], v[134:135], v[50:51] op_sel_hi:[0,1,1]
	v_pk_fma_f32 v[52:53], v[130:131], v[136:137], v[52:53] op_sel_hi:[0,1,1]
	v_pk_fma_f32 v[54:55], v[130:131], v[138:139], v[54:55] op_sel_hi:[0,1,1]
	v_pk_fma_f32 v[56:57], v[130:131], v[140:141], v[56:57] op_sel_hi:[0,1,1]
	v_cvt_scalef32_pk_f32_fp4 v[134:135], v149, 1.0
	v_cvt_scalef32_pk_f32_fp4 v[136:137], v149, 1.0 op_sel:[1,0,0]
	v_cvt_scalef32_pk_f32_fp4 v[138:139], v149, 1.0 op_sel:[0,1,0]
	v_cvt_scalef32_pk_f32_fp4 v[140:141], v149, 1.0 op_sel:[1,1,0]
	v_pk_fma_f32 v[58:59], v[130:131], v[134:135], v[58:59] op_sel_hi:[0,1,1]
	v_pk_fma_f32 v[60:61], v[130:131], v[136:137], v[60:61] op_sel_hi:[0,1,1]
	v_pk_fma_f32 v[62:63], v[130:131], v[138:139], v[62:63] op_sel_hi:[0,1,1]
	v_pk_fma_f32 v[64:65], v[130:131], v[140:141], v[64:65] op_sel_hi:[0,1,1]
	ds_read_b32 v130, v132 offset:80
	s_waitcnt vmcnt(5)
	v_cvt_scalef32_pk_f32_fp4 v[134:135], v150, 1.0
	v_cvt_scalef32_pk_f32_fp4 v[136:137], v150, 1.0 op_sel:[1,0,0]
	v_cvt_scalef32_pk_f32_fp4 v[138:139], v150, 1.0 op_sel:[0,1,0]
	v_cvt_scalef32_pk_f32_fp4 v[140:141], v150, 1.0 op_sel:[1,1,0]
	s_waitcnt lgkmcnt(0)
	v_pk_fma_f32 v[128:129], v[130:131], v[134:135], v[128:129] op_sel_hi:[0,1,1]
	v_pk_fma_f32 v[126:127], v[130:131], v[136:137], v[126:127] op_sel_hi:[0,1,1]
	v_pk_fma_f32 v[122:123], v[130:131], v[138:139], v[122:123] op_sel_hi:[0,1,1]
	v_pk_fma_f32 v[120:121], v[130:131], v[140:141], v[120:121] op_sel_hi:[0,1,1]
	v_cvt_scalef32_pk_f32_fp4 v[134:135], v151, 1.0
	v_cvt_scalef32_pk_f32_fp4 v[136:137], v151, 1.0 op_sel:[1,0,0]
	v_cvt_scalef32_pk_f32_fp4 v[138:139], v151, 1.0 op_sel:[0,1,0]
	v_cvt_scalef32_pk_f32_fp4 v[140:141], v151, 1.0 op_sel:[1,1,0]
	v_pk_fma_f32 v[118:119], v[130:131], v[134:135], v[118:119] op_sel_hi:[0,1,1]
	v_pk_fma_f32 v[116:117], v[130:131], v[136:137], v[116:117] op_sel_hi:[0,1,1]
	v_pk_fma_f32 v[114:115], v[130:131], v[138:139], v[114:115] op_sel_hi:[0,1,1]
	v_pk_fma_f32 v[112:113], v[130:131], v[140:141], v[112:113] op_sel_hi:[0,1,1]
	v_cvt_scalef32_pk_f32_fp4 v[134:135], v152, 1.0
	v_cvt_scalef32_pk_f32_fp4 v[136:137], v152, 1.0 op_sel:[1,0,0]
	v_cvt_scalef32_pk_f32_fp4 v[138:139], v152, 1.0 op_sel:[0,1,0]
	v_cvt_scalef32_pk_f32_fp4 v[140:141], v152, 1.0 op_sel:[1,1,0]
	v_pk_fma_f32 v[80:81], v[130:131], v[134:135], v[80:81] op_sel_hi:[0,1,1]
	v_pk_fma_f32 v[78:79], v[130:131], v[136:137], v[78:79] op_sel_hi:[0,1,1]
	v_pk_fma_f32 v[76:77], v[130:131], v[138:139], v[76:77] op_sel_hi:[0,1,1]
	v_pk_fma_f32 v[74:75], v[130:131], v[140:141], v[74:75] op_sel_hi:[0,1,1]
	v_cvt_scalef32_pk_f32_fp4 v[134:135], v153, 1.0
	v_cvt_scalef32_pk_f32_fp4 v[136:137], v153, 1.0 op_sel:[1,0,0]
	v_cvt_scalef32_pk_f32_fp4 v[138:139], v153, 1.0 op_sel:[0,1,0]
	v_cvt_scalef32_pk_f32_fp4 v[140:141], v153, 1.0 op_sel:[1,1,0]
	v_pk_fma_f32 v[72:73], v[130:131], v[134:135], v[72:73] op_sel_hi:[0,1,1]
	v_pk_fma_f32 v[70:71], v[130:131], v[136:137], v[70:71] op_sel_hi:[0,1,1]
	v_pk_fma_f32 v[68:69], v[130:131], v[138:139], v[68:69] op_sel_hi:[0,1,1]
	v_pk_fma_f32 v[66:67], v[130:131], v[140:141], v[66:67] op_sel_hi:[0,1,1]
	s_waitcnt vmcnt(4)
	v_cvt_scalef32_pk_f32_fp4 v[134:135], v232, 1.0
	v_cvt_scalef32_pk_f32_fp4 v[136:137], v232, 1.0 op_sel:[1,0,0]
	v_cvt_scalef32_pk_f32_fp4 v[138:139], v232, 1.0 op_sel:[0,1,0]
	v_cvt_scalef32_pk_f32_fp4 v[140:141], v232, 1.0 op_sel:[1,1,0]
	v_pk_fma_f32 v[34:35], v[130:131], v[134:135], v[34:35] op_sel_hi:[0,1,1]
	v_pk_fma_f32 v[36:37], v[130:131], v[136:137], v[36:37] op_sel_hi:[0,1,1]
	v_pk_fma_f32 v[38:39], v[130:131], v[138:139], v[38:39] op_sel_hi:[0,1,1]
	v_pk_fma_f32 v[40:41], v[130:131], v[140:141], v[40:41] op_sel_hi:[0,1,1]
	v_cvt_scalef32_pk_f32_fp4 v[134:135], v233, 1.0
	v_cvt_scalef32_pk_f32_fp4 v[136:137], v233, 1.0 op_sel:[1,0,0]
	v_cvt_scalef32_pk_f32_fp4 v[138:139], v233, 1.0 op_sel:[0,1,0]
	v_cvt_scalef32_pk_f32_fp4 v[140:141], v233, 1.0 op_sel:[1,1,0]
	v_pk_fma_f32 v[42:43], v[130:131], v[134:135], v[42:43] op_sel_hi:[0,1,1]
	v_pk_fma_f32 v[44:45], v[130:131], v[136:137], v[44:45] op_sel_hi:[0,1,1]
	v_pk_fma_f32 v[46:47], v[130:131], v[138:139], v[46:47] op_sel_hi:[0,1,1]
	v_pk_fma_f32 v[48:49], v[130:131], v[140:141], v[48:49] op_sel_hi:[0,1,1]
	v_cvt_scalef32_pk_f32_fp4 v[134:135], v234, 1.0
	v_cvt_scalef32_pk_f32_fp4 v[136:137], v234, 1.0 op_sel:[1,0,0]
	v_cvt_scalef32_pk_f32_fp4 v[138:139], v234, 1.0 op_sel:[0,1,0]
	v_cvt_scalef32_pk_f32_fp4 v[140:141], v234, 1.0 op_sel:[1,1,0]
	v_pk_fma_f32 v[50:51], v[130:131], v[134:135], v[50:51] op_sel_hi:[0,1,1]
	v_pk_fma_f32 v[52:53], v[130:131], v[136:137], v[52:53] op_sel_hi:[0,1,1]
	v_pk_fma_f32 v[54:55], v[130:131], v[138:139], v[54:55] op_sel_hi:[0,1,1]
	v_pk_fma_f32 v[56:57], v[130:131], v[140:141], v[56:57] op_sel_hi:[0,1,1]
	v_cvt_scalef32_pk_f32_fp4 v[134:135], v235, 1.0
	v_cvt_scalef32_pk_f32_fp4 v[136:137], v235, 1.0 op_sel:[1,0,0]
	v_cvt_scalef32_pk_f32_fp4 v[138:139], v235, 1.0 op_sel:[0,1,0]
	v_cvt_scalef32_pk_f32_fp4 v[140:141], v235, 1.0 op_sel:[1,1,0]
	v_pk_fma_f32 v[58:59], v[130:131], v[134:135], v[58:59] op_sel_hi:[0,1,1]
	v_pk_fma_f32 v[60:61], v[130:131], v[136:137], v[60:61] op_sel_hi:[0,1,1]
	v_pk_fma_f32 v[62:63], v[130:131], v[138:139], v[62:63] op_sel_hi:[0,1,1]
	v_pk_fma_f32 v[64:65], v[130:131], v[140:141], v[64:65] op_sel_hi:[0,1,1]
	ds_read_b32 v130, v132 offset:96
	s_waitcnt vmcnt(3)
	v_cvt_scalef32_pk_f32_fp4 v[134:135], v236, 1.0
	v_cvt_scalef32_pk_f32_fp4 v[136:137], v236, 1.0 op_sel:[1,0,0]
	v_cvt_scalef32_pk_f32_fp4 v[138:139], v236, 1.0 op_sel:[0,1,0]
	v_cvt_scalef32_pk_f32_fp4 v[140:141], v236, 1.0 op_sel:[1,1,0]
	s_waitcnt lgkmcnt(0)
	v_pk_fma_f32 v[128:129], v[130:131], v[134:135], v[128:129] op_sel_hi:[0,1,1]
	v_pk_fma_f32 v[126:127], v[130:131], v[136:137], v[126:127] op_sel_hi:[0,1,1]
	v_pk_fma_f32 v[122:123], v[130:131], v[138:139], v[122:123] op_sel_hi:[0,1,1]
	v_pk_fma_f32 v[120:121], v[130:131], v[140:141], v[120:121] op_sel_hi:[0,1,1]
	v_cvt_scalef32_pk_f32_fp4 v[134:135], v237, 1.0
	v_cvt_scalef32_pk_f32_fp4 v[136:137], v237, 1.0 op_sel:[1,0,0]
	v_cvt_scalef32_pk_f32_fp4 v[138:139], v237, 1.0 op_sel:[0,1,0]
	v_cvt_scalef32_pk_f32_fp4 v[140:141], v237, 1.0 op_sel:[1,1,0]
	v_pk_fma_f32 v[118:119], v[130:131], v[134:135], v[118:119] op_sel_hi:[0,1,1]
	v_pk_fma_f32 v[116:117], v[130:131], v[136:137], v[116:117] op_sel_hi:[0,1,1]
	v_pk_fma_f32 v[114:115], v[130:131], v[138:139], v[114:115] op_sel_hi:[0,1,1]
	v_pk_fma_f32 v[112:113], v[130:131], v[140:141], v[112:113] op_sel_hi:[0,1,1]
	v_cvt_scalef32_pk_f32_fp4 v[134:135], v238, 1.0
	v_cvt_scalef32_pk_f32_fp4 v[136:137], v238, 1.0 op_sel:[1,0,0]
	v_cvt_scalef32_pk_f32_fp4 v[138:139], v238, 1.0 op_sel:[0,1,0]
	v_cvt_scalef32_pk_f32_fp4 v[140:141], v238, 1.0 op_sel:[1,1,0]
	v_pk_fma_f32 v[80:81], v[130:131], v[134:135], v[80:81] op_sel_hi:[0,1,1]
	v_pk_fma_f32 v[78:79], v[130:131], v[136:137], v[78:79] op_sel_hi:[0,1,1]
	v_pk_fma_f32 v[76:77], v[130:131], v[138:139], v[76:77] op_sel_hi:[0,1,1]
	v_pk_fma_f32 v[74:75], v[130:131], v[140:141], v[74:75] op_sel_hi:[0,1,1]
	v_cvt_scalef32_pk_f32_fp4 v[134:135], v239, 1.0
	v_cvt_scalef32_pk_f32_fp4 v[136:137], v239, 1.0 op_sel:[1,0,0]
	v_cvt_scalef32_pk_f32_fp4 v[138:139], v239, 1.0 op_sel:[0,1,0]
	v_cvt_scalef32_pk_f32_fp4 v[140:141], v239, 1.0 op_sel:[1,1,0]
	v_pk_fma_f32 v[72:73], v[130:131], v[134:135], v[72:73] op_sel_hi:[0,1,1]
	v_pk_fma_f32 v[70:71], v[130:131], v[136:137], v[70:71] op_sel_hi:[0,1,1]
	v_pk_fma_f32 v[68:69], v[130:131], v[138:139], v[68:69] op_sel_hi:[0,1,1]
	v_pk_fma_f32 v[66:67], v[130:131], v[140:141], v[66:67] op_sel_hi:[0,1,1]
	s_waitcnt vmcnt(2)
	v_cvt_scalef32_pk_f32_fp4 v[134:135], v240, 1.0
	v_cvt_scalef32_pk_f32_fp4 v[136:137], v240, 1.0 op_sel:[1,0,0]
	v_cvt_scalef32_pk_f32_fp4 v[138:139], v240, 1.0 op_sel:[0,1,0]
	v_cvt_scalef32_pk_f32_fp4 v[140:141], v240, 1.0 op_sel:[1,1,0]
	v_pk_fma_f32 v[34:35], v[130:131], v[134:135], v[34:35] op_sel_hi:[0,1,1]
	v_pk_fma_f32 v[36:37], v[130:131], v[136:137], v[36:37] op_sel_hi:[0,1,1]
	v_pk_fma_f32 v[38:39], v[130:131], v[138:139], v[38:39] op_sel_hi:[0,1,1]
	v_pk_fma_f32 v[40:41], v[130:131], v[140:141], v[40:41] op_sel_hi:[0,1,1]
	v_cvt_scalef32_pk_f32_fp4 v[134:135], v241, 1.0
	v_cvt_scalef32_pk_f32_fp4 v[136:137], v241, 1.0 op_sel:[1,0,0]
	v_cvt_scalef32_pk_f32_fp4 v[138:139], v241, 1.0 op_sel:[0,1,0]
	v_cvt_scalef32_pk_f32_fp4 v[140:141], v241, 1.0 op_sel:[1,1,0]
	v_pk_fma_f32 v[42:43], v[130:131], v[134:135], v[42:43] op_sel_hi:[0,1,1]
	v_pk_fma_f32 v[44:45], v[130:131], v[136:137], v[44:45] op_sel_hi:[0,1,1]
	v_pk_fma_f32 v[46:47], v[130:131], v[138:139], v[46:47] op_sel_hi:[0,1,1]
	v_pk_fma_f32 v[48:49], v[130:131], v[140:141], v[48:49] op_sel_hi:[0,1,1]
	v_cvt_scalef32_pk_f32_fp4 v[134:135], v242, 1.0
	v_cvt_scalef32_pk_f32_fp4 v[136:137], v242, 1.0 op_sel:[1,0,0]
	v_cvt_scalef32_pk_f32_fp4 v[138:139], v242, 1.0 op_sel:[0,1,0]
	v_cvt_scalef32_pk_f32_fp4 v[140:141], v242, 1.0 op_sel:[1,1,0]
	v_pk_fma_f32 v[50:51], v[130:131], v[134:135], v[50:51] op_sel_hi:[0,1,1]
	v_pk_fma_f32 v[52:53], v[130:131], v[136:137], v[52:53] op_sel_hi:[0,1,1]
	v_pk_fma_f32 v[54:55], v[130:131], v[138:139], v[54:55] op_sel_hi:[0,1,1]
	v_pk_fma_f32 v[56:57], v[130:131], v[140:141], v[56:57] op_sel_hi:[0,1,1]
	v_cvt_scalef32_pk_f32_fp4 v[134:135], v243, 1.0
	v_cvt_scalef32_pk_f32_fp4 v[136:137], v243, 1.0 op_sel:[1,0,0]
	v_cvt_scalef32_pk_f32_fp4 v[138:139], v243, 1.0 op_sel:[0,1,0]
	v_cvt_scalef32_pk_f32_fp4 v[140:141], v243, 1.0 op_sel:[1,1,0]
	v_pk_fma_f32 v[58:59], v[130:131], v[134:135], v[58:59] op_sel_hi:[0,1,1]
	v_pk_fma_f32 v[60:61], v[130:131], v[136:137], v[60:61] op_sel_hi:[0,1,1]
	v_pk_fma_f32 v[62:63], v[130:131], v[138:139], v[62:63] op_sel_hi:[0,1,1]
	v_pk_fma_f32 v[64:65], v[130:131], v[140:141], v[64:65] op_sel_hi:[0,1,1]
	ds_read_b32 v130, v132 offset:112
	s_waitcnt vmcnt(1)
	v_cvt_scalef32_pk_f32_fp4 v[134:135], v244, 1.0
	v_cvt_scalef32_pk_f32_fp4 v[136:137], v244, 1.0 op_sel:[1,0,0]
	v_cvt_scalef32_pk_f32_fp4 v[138:139], v244, 1.0 op_sel:[0,1,0]
	v_cvt_scalef32_pk_f32_fp4 v[140:141], v244, 1.0 op_sel:[1,1,0]
	s_waitcnt lgkmcnt(0)
	v_pk_fma_f32 v[128:129], v[130:131], v[134:135], v[128:129] op_sel_hi:[0,1,1]
	v_pk_fma_f32 v[126:127], v[130:131], v[136:137], v[126:127] op_sel_hi:[0,1,1]
	v_pk_fma_f32 v[122:123], v[130:131], v[138:139], v[122:123] op_sel_hi:[0,1,1]
	v_pk_fma_f32 v[120:121], v[130:131], v[140:141], v[120:121] op_sel_hi:[0,1,1]
	v_cvt_scalef32_pk_f32_fp4 v[134:135], v245, 1.0
	v_cvt_scalef32_pk_f32_fp4 v[136:137], v245, 1.0 op_sel:[1,0,0]
	v_cvt_scalef32_pk_f32_fp4 v[138:139], v245, 1.0 op_sel:[0,1,0]
	v_cvt_scalef32_pk_f32_fp4 v[140:141], v245, 1.0 op_sel:[1,1,0]
	v_pk_fma_f32 v[118:119], v[130:131], v[134:135], v[118:119] op_sel_hi:[0,1,1]
	v_pk_fma_f32 v[116:117], v[130:131], v[136:137], v[116:117] op_sel_hi:[0,1,1]
	v_pk_fma_f32 v[114:115], v[130:131], v[138:139], v[114:115] op_sel_hi:[0,1,1]
	v_pk_fma_f32 v[112:113], v[130:131], v[140:141], v[112:113] op_sel_hi:[0,1,1]
	v_cvt_scalef32_pk_f32_fp4 v[134:135], v246, 1.0
	v_cvt_scalef32_pk_f32_fp4 v[136:137], v246, 1.0 op_sel:[1,0,0]
	v_cvt_scalef32_pk_f32_fp4 v[138:139], v246, 1.0 op_sel:[0,1,0]
	v_cvt_scalef32_pk_f32_fp4 v[140:141], v246, 1.0 op_sel:[1,1,0]
	v_pk_fma_f32 v[80:81], v[130:131], v[134:135], v[80:81] op_sel_hi:[0,1,1]
	v_pk_fma_f32 v[78:79], v[130:131], v[136:137], v[78:79] op_sel_hi:[0,1,1]
	v_pk_fma_f32 v[76:77], v[130:131], v[138:139], v[76:77] op_sel_hi:[0,1,1]
	v_pk_fma_f32 v[74:75], v[130:131], v[140:141], v[74:75] op_sel_hi:[0,1,1]
	v_cvt_scalef32_pk_f32_fp4 v[134:135], v247, 1.0
	v_cvt_scalef32_pk_f32_fp4 v[136:137], v247, 1.0 op_sel:[1,0,0]
	v_cvt_scalef32_pk_f32_fp4 v[138:139], v247, 1.0 op_sel:[0,1,0]
	v_cvt_scalef32_pk_f32_fp4 v[140:141], v247, 1.0 op_sel:[1,1,0]
	v_pk_fma_f32 v[72:73], v[130:131], v[134:135], v[72:73] op_sel_hi:[0,1,1]
	v_pk_fma_f32 v[70:71], v[130:131], v[136:137], v[70:71] op_sel_hi:[0,1,1]
	v_pk_fma_f32 v[68:69], v[130:131], v[138:139], v[68:69] op_sel_hi:[0,1,1]
	v_pk_fma_f32 v[66:67], v[130:131], v[140:141], v[66:67] op_sel_hi:[0,1,1]
	s_waitcnt vmcnt(0)
	v_cvt_scalef32_pk_f32_fp4 v[134:135], v228, 1.0
	v_cvt_scalef32_pk_f32_fp4 v[136:137], v228, 1.0 op_sel:[1,0,0]
	v_cvt_scalef32_pk_f32_fp4 v[138:139], v228, 1.0 op_sel:[0,1,0]
	v_cvt_scalef32_pk_f32_fp4 v[140:141], v228, 1.0 op_sel:[1,1,0]
	v_pk_fma_f32 v[34:35], v[130:131], v[134:135], v[34:35] op_sel_hi:[0,1,1]
	v_pk_fma_f32 v[36:37], v[130:131], v[136:137], v[36:37] op_sel_hi:[0,1,1]
	v_pk_fma_f32 v[38:39], v[130:131], v[138:139], v[38:39] op_sel_hi:[0,1,1]
	v_pk_fma_f32 v[40:41], v[130:131], v[140:141], v[40:41] op_sel_hi:[0,1,1]
	v_cvt_scalef32_pk_f32_fp4 v[134:135], v229, 1.0
	v_cvt_scalef32_pk_f32_fp4 v[136:137], v229, 1.0 op_sel:[1,0,0]
	v_cvt_scalef32_pk_f32_fp4 v[138:139], v229, 1.0 op_sel:[0,1,0]
	v_cvt_scalef32_pk_f32_fp4 v[140:141], v229, 1.0 op_sel:[1,1,0]
	v_pk_fma_f32 v[42:43], v[130:131], v[134:135], v[42:43] op_sel_hi:[0,1,1]
	v_pk_fma_f32 v[44:45], v[130:131], v[136:137], v[44:45] op_sel_hi:[0,1,1]
	v_pk_fma_f32 v[46:47], v[130:131], v[138:139], v[46:47] op_sel_hi:[0,1,1]
	v_pk_fma_f32 v[48:49], v[130:131], v[140:141], v[48:49] op_sel_hi:[0,1,1]
	v_cvt_scalef32_pk_f32_fp4 v[134:135], v230, 1.0
	v_cvt_scalef32_pk_f32_fp4 v[136:137], v230, 1.0 op_sel:[1,0,0]
	v_cvt_scalef32_pk_f32_fp4 v[138:139], v230, 1.0 op_sel:[0,1,0]
	v_cvt_scalef32_pk_f32_fp4 v[140:141], v230, 1.0 op_sel:[1,1,0]
	v_pk_fma_f32 v[50:51], v[130:131], v[134:135], v[50:51] op_sel_hi:[0,1,1]
	v_pk_fma_f32 v[52:53], v[130:131], v[136:137], v[52:53] op_sel_hi:[0,1,1]
	v_pk_fma_f32 v[54:55], v[130:131], v[138:139], v[54:55] op_sel_hi:[0,1,1]
	v_pk_fma_f32 v[56:57], v[130:131], v[140:141], v[56:57] op_sel_hi:[0,1,1]
	v_cvt_scalef32_pk_f32_fp4 v[134:135], v231, 1.0
	v_cvt_scalef32_pk_f32_fp4 v[136:137], v231, 1.0 op_sel:[1,0,0]
	v_cvt_scalef32_pk_f32_fp4 v[138:139], v231, 1.0 op_sel:[0,1,0]
	v_cvt_scalef32_pk_f32_fp4 v[140:141], v231, 1.0 op_sel:[1,1,0]
	v_pk_fma_f32 v[58:59], v[130:131], v[134:135], v[58:59] op_sel_hi:[0,1,1]
	v_pk_fma_f32 v[60:61], v[130:131], v[136:137], v[60:61] op_sel_hi:[0,1,1]
	v_pk_fma_f32 v[62:63], v[130:131], v[138:139], v[62:63] op_sel_hi:[0,1,1]
	v_pk_fma_f32 v[64:65], v[130:131], v[140:141], v[64:65] op_sel_hi:[0,1,1]
	v_lshrrev_b32_e32 v2, 1, v125
	v_and_b32_e32 v3, 1, v125
	v_lshlrev_b32_e32 v2, 9, v2
	v_lshl_add_u32 v2, v3, 4, v2
	v_lshlrev_b64 v[94:95], 10, v[94:95]
	v_or_b32_e32 v94, v94, v82
	v_add_u32_e32 v94, v94, v2
	v_lshlrev_b64 v[130:131], 2, v[94:95]
	v_lshl_add_u64 v[132:133], s[18:19], 0, v[130:131]
	global_load_dwordx4 v[4:7], v[132:133], off
	global_load_dwordx4 v[8:11], v[132:133], off offset:16
	global_load_dwordx4 v[12:15], v[132:133], off offset:32
	global_load_dwordx4 v[16:19], v[132:133], off offset:48
	v_lshlrev_b32_e32 v2, 2, v2
	v_mov_b32_e32 v3, 0
	v_lshl_add_u64 v[20:21], v[88:89], 0, v[2:3]
	global_load_dwordx4 v[134:137], v[20:21], off
	global_load_dwordx4 v[138:141], v[20:21], off offset:16
	global_load_dwordx4 v[142:145], v[20:21], off offset:32
	global_load_dwordx4 v[146:149], v[20:21], off offset:48
	v_readlane_b32 s60, v254, 29
	v_readlane_b32 s61, v254, 30
	v_readlane_b32 s62, v254, 31
	v_readlane_b32 s63, v254, 32
	v_lshl_add_u64 v[22:23], s[20:21], 0, v[130:131]
	v_lshl_add_u64 v[26:27], v[94:95], 1, s[16:17]
	v_permlane16_swap_b32_e32 v128, v80
	v_permlane16_swap_b32_e32 v129, v81
	v_pk_add_f32 v[128:129], v[128:129], v[80:81]
	v_permlane16_swap_b32_e32 v126, v78
	v_permlane16_swap_b32_e32 v127, v79
	v_pk_add_f32 v[126:127], v[126:127], v[78:79]
	v_permlane16_swap_b32_e32 v122, v76
	v_permlane16_swap_b32_e32 v123, v77
	v_pk_add_f32 v[122:123], v[122:123], v[76:77]
	v_permlane16_swap_b32_e32 v120, v74
	v_permlane16_swap_b32_e32 v121, v75
	v_pk_add_f32 v[120:121], v[120:121], v[74:75]
	v_permlane16_swap_b32_e32 v118, v72
	v_permlane16_swap_b32_e32 v119, v73
	v_pk_add_f32 v[118:119], v[118:119], v[72:73]
	v_permlane16_swap_b32_e32 v116, v70
	v_permlane16_swap_b32_e32 v117, v71
	v_pk_add_f32 v[116:117], v[116:117], v[70:71]
	v_permlane16_swap_b32_e32 v114, v68
	v_permlane16_swap_b32_e32 v115, v69
	v_pk_add_f32 v[114:115], v[114:115], v[68:69]
	v_permlane16_swap_b32_e32 v112, v66
	v_permlane16_swap_b32_e32 v113, v67
	v_pk_add_f32 v[112:113], v[112:113], v[66:67]
	v_permlane16_swap_b32_e32 v34, v50
	v_permlane16_swap_b32_e32 v35, v51
	v_pk_add_f32 v[34:35], v[34:35], v[50:51]
	v_permlane16_swap_b32_e32 v36, v52
	v_permlane16_swap_b32_e32 v37, v53
	v_pk_add_f32 v[36:37], v[36:37], v[52:53]
	v_permlane16_swap_b32_e32 v38, v54
	v_permlane16_swap_b32_e32 v39, v55
	v_pk_add_f32 v[38:39], v[38:39], v[54:55]
	v_permlane16_swap_b32_e32 v40, v56
	v_permlane16_swap_b32_e32 v41, v57
	v_pk_add_f32 v[40:41], v[40:41], v[56:57]
	v_permlane16_swap_b32_e32 v42, v58
	v_permlane16_swap_b32_e32 v43, v59
	v_pk_add_f32 v[42:43], v[42:43], v[58:59]
	v_permlane16_swap_b32_e32 v44, v60
	v_permlane16_swap_b32_e32 v45, v61
	v_pk_add_f32 v[44:45], v[44:45], v[60:61]
	v_permlane16_swap_b32_e32 v46, v62
	v_permlane16_swap_b32_e32 v47, v63
	v_pk_add_f32 v[46:47], v[46:47], v[62:63]
	v_permlane16_swap_b32_e32 v48, v64
	v_permlane16_swap_b32_e32 v49, v65
	v_pk_add_f32 v[48:49], v[48:49], v[64:65]
	v_permlane32_swap_b32_e32 v128, v34
	v_permlane32_swap_b32_e32 v129, v35
	v_pk_add_f32 v[128:129], v[128:129], v[34:35]
	v_permlane32_swap_b32_e32 v126, v36
	v_permlane32_swap_b32_e32 v127, v37
	v_pk_add_f32 v[126:127], v[126:127], v[36:37]
	v_permlane32_swap_b32_e32 v122, v38
	v_permlane32_swap_b32_e32 v123, v39
	v_pk_add_f32 v[122:123], v[122:123], v[38:39]
	v_permlane32_swap_b32_e32 v120, v40
	v_permlane32_swap_b32_e32 v121, v41
	v_pk_add_f32 v[120:121], v[120:121], v[40:41]
	v_permlane32_swap_b32_e32 v118, v42
	v_permlane32_swap_b32_e32 v119, v43
	v_pk_add_f32 v[118:119], v[118:119], v[42:43]
	v_permlane32_swap_b32_e32 v116, v44
	v_permlane32_swap_b32_e32 v117, v45
	v_pk_add_f32 v[116:117], v[116:117], v[44:45]
	v_permlane32_swap_b32_e32 v114, v46
	v_permlane32_swap_b32_e32 v115, v47
	v_pk_add_f32 v[114:115], v[114:115], v[46:47]
	v_permlane32_swap_b32_e32 v112, v48
	v_permlane32_swap_b32_e32 v113, v49
	v_pk_add_f32 v[112:113], v[112:113], v[48:49]
	v_lshl_add_u64 v[24:25], s[60:61], 0, v[130:131]
	s_waitcnt vmcnt(4)
	v_pk_add_f32 v[228:229], v[4:5], v[128:129]
	v_pk_add_f32 v[230:231], v[6:7], v[126:127]
	v_pk_add_f32 v[232:233], v[8:9], v[122:123]
	v_pk_add_f32 v[234:235], v[10:11], v[120:121]
	v_pk_add_f32 v[236:237], v[12:13], v[118:119]
	v_pk_add_f32 v[238:239], v[14:15], v[116:117]
	v_pk_add_f32 v[240:241], v[16:17], v[114:115]
	v_pk_add_f32 v[242:243], v[18:19], v[112:113]
	v_pk_mul_f32 v[244:245], v[228:229], v[228:229]
	v_pk_fma_f32 v[244:245], v[230:231], v[230:231], v[244:245]
	v_pk_fma_f32 v[244:245], v[232:233], v[232:233], v[244:245]
	v_pk_fma_f32 v[244:245], v[234:235], v[234:235], v[244:245]
	v_pk_fma_f32 v[244:245], v[236:237], v[236:237], v[244:245]
	v_pk_fma_f32 v[244:245], v[238:239], v[238:239], v[244:245]
	v_pk_fma_f32 v[244:245], v[240:241], v[240:241], v[244:245]
	v_pk_fma_f32 v[244:245], v[242:243], v[242:243], v[244:245]
	v_add_f32_e32 v244, v244, v245
	ds_bpermute_b32 v245, v207, v244
	s_waitcnt lgkmcnt(0)
	v_add_f32_e32 v244, v244, v245
	ds_bpermute_b32 v245, v208, v244
	s_waitcnt lgkmcnt(0)
	v_add_f32_e32 v244, v244, v245
	ds_bpermute_b32 v245, v209, v244
	s_waitcnt lgkmcnt(0)
	v_add_f32_e32 v244, v244, v245
	ds_bpermute_b32 v245, v210, v244
	s_waitcnt lgkmcnt(0)
	v_add_f32_e32 v244, v244, v245
	ds_bpermute_b32 v245, v211, v244
	s_waitcnt lgkmcnt(0)
	v_add_f32_e32 v244, v244, v245
	ds_bpermute_b32 v245, v212, v244
	s_waitcnt lgkmcnt(0)
	v_add_f32_e32 v244, v244, v245
	v_fmamk_f32 v244, v244, 0x3a800000, v172
	v_mul_f32_e32 v245, 0x4b800000, v244
	v_cmp_gt_f32_e32 vcc, s96, v244
	s_nop 1
	v_cndmask_b32_e32 v244, v244, v245, vcc
	v_rsq_f32_e32 v244, v244
	s_nop 0
	v_mul_f32_e32 v245, 0x45800000, v244
	v_cndmask_b32_e32 v246, v244, v245, vcc
	s_waitcnt vmcnt(0)
	v_pk_mul_f32 v[134:135], v[246:247], v[134:135] op_sel_hi:[0,1]
	v_pk_mul_f32 v[136:137], v[246:247], v[136:137] op_sel_hi:[0,1]
	v_pk_mul_f32 v[138:139], v[246:247], v[138:139] op_sel_hi:[0,1]
	v_pk_mul_f32 v[140:141], v[246:247], v[140:141] op_sel_hi:[0,1]
	v_pk_mul_f32 v[142:143], v[246:247], v[142:143] op_sel_hi:[0,1]
	v_pk_mul_f32 v[144:145], v[246:247], v[144:145] op_sel_hi:[0,1]
	v_pk_mul_f32 v[146:147], v[246:247], v[146:147] op_sel_hi:[0,1]
	v_pk_mul_f32 v[148:149], v[246:247], v[148:149] op_sel_hi:[0,1]
	v_pk_mul_f32 v[134:135], v[228:229], v[134:135]
	v_pk_mul_f32 v[136:137], v[230:231], v[136:137]
	v_pk_mul_f32 v[138:139], v[232:233], v[138:139]
	v_pk_mul_f32 v[140:141], v[234:235], v[140:141]
	v_pk_mul_f32 v[142:143], v[236:237], v[142:143]
	v_pk_mul_f32 v[144:145], v[238:239], v[144:145]
	v_pk_mul_f32 v[146:147], v[240:241], v[146:147]
	v_pk_mul_f32 v[148:149], v[242:243], v[148:149]
	s_andn2_b64 vcc, exec, s[22:23]
	s_cbranch_vccnz .Lpe_mid
	global_store_dwordx4 v[24:25], v[134:137], off
	global_store_dwordx4 v[24:25], v[138:141], off offset:16
	global_store_dwordx4 v[24:25], v[142:145], off offset:32
	global_store_dwordx4 v[24:25], v[146:149], off offset:48
	s_branch .Lpe_done
